# half tiles (64x128) of phase 4b and 5b GEMMs converted to the 16x16x32 swizzled-LDS k-loop with 2-deep prefetch
# speedup vs baseline: 1.0173x; 1.0066x over previous
.LBB0_725:
	s_cmpk_gt_i32 s51, 0x3ff
	s_mov_b64 s[24:25], -1
	s_cbranch_scc0 .LBB0_765
	s_lshl_b32 s14, s51, 3
	s_add_i32 s14, s14, 0x7fffe000
	s_and_b32 s14, s14, 0x7fffffc0
	s_addk_i32 s14, 0x4000
	v_or_b32_e32 v0, s14, v105
	v_lshlrev_b32_e32 v48, 11, v0
	v_mov_b32_e32 v49, v65
	v_lshl_add_u64 v[0:1], v[66:67], 0, v[48:49]
	s_lshl_b32 s15, s51, 7
	s_and_b32 s15, s15, 0x380
	v_add_lshl_u32 v64, s15, v105, 11
	v_lshl_add_u64 v[70:71], v[68:69], 0, v[64:65]
	v_readfirstlane_b32 s98, v66
	v_readfirstlane_b32 s99, v67
	v_readfirstlane_b32 s100, v68
	v_readfirstlane_b32 s101, v69
	s_mul_i32 s25, s14, 0x800
	s_add_u32 s98, s98, s25
	s_addc_u32 s99, s99, 0
	s_mul_i32 s25, s15, 0x800
	s_add_u32 s100, s100, s25
	s_addc_u32 s101, s101, 0
	v_lshrrev_b32_e32 v246, 3, v100
	v_and_b32_e32 v247, 7, v100
	v_bfe_u32 v244, v100, 4, 3
	v_xor_b32_e32 v244, v244, v247
	v_lshlrev_b32_e32 v244, 4, v244
	v_lshl_or_b32 v110, v246, 7, v244
	v_lshlrev_b32_e32 v245, 4, v247
	v_mul_u32_u24_e32 v79, 0x800, v246
	v_add_u32_e32 v79, v79, v245
	v_add_u32_e32 v80, 0x10000, v79
	v_mul_u32_u24_e32 v93, 0x800, v246
	v_add_u32_e32 v93, v93, v245
	v_add_u32_e32 v94, 0x10000, v93
	v_add_u32_e32 v95, 0x20000, v93
	v_add_u32_e32 v109, 0x30000, v93
	v_and_b32_e32 v244, 15, v100
	v_bfe_u32 v245, v100, 4, 2
	v_bfe_u32 v246, v100, 1, 3
	v_xor_b32_e32 v247, v245, v246
	v_lshlrev_b32_e32 v247, 4, v247
	v_lshl_or_b32 v247, v244, 7, v247
	v_bfe_u32 v246, v100, 7, 1
	v_lshl_add_u32 v239, v246, 12, v247
	v_xor_b32_e32 v240, 64, v239
	v_bfe_u32 v246, v100, 6, 1
	v_lshl_add_u32 v241, v246, 13, v247
	v_add_u32_e32 v241, 0x4000, v241
	v_xor_b32_e32 v242, 64, v241
	v_bfe_u32 v247, v100, 7, 1
	v_lshlrev_b32_e32 v247, 5, v247
	v_lshl_add_u32 v247, v245, 2, v247
	v_mul_u32_u24_e32 v247, 0x84, v247
	v_lshl_add_u32 v247, v246, 6, v247
	v_add_u32_e32 v247, v247, v244
	v_lshlrev_b32_e32 v243, 2, v247
	global_load_dwordx4 v[138:141], v79, s[98:99]
	global_load_dwordx4 v[142:145], v80, s[98:99]
	global_load_dwordx4 v[154:157], v93, s[100:101]
	global_load_dwordx4 v[158:161], v94, s[100:101]
	global_load_dwordx4 v[162:165], v95, s[100:101]
	global_load_dwordx4 v[166:169], v109, s[100:101]
	global_load_dwordx4 v[170:173], v79, s[98:99] offset:128
	global_load_dwordx4 v[174:177], v80, s[98:99] offset:128
	global_load_dwordx4 v[178:181], v93, s[100:101] offset:128
	global_load_dwordx4 v[182:185], v94, s[100:101] offset:128
	global_load_dwordx4 v[186:189], v95, s[100:101] offset:128
	global_load_dwordx4 v[190:193], v109, s[100:101] offset:128
	s_barrier
	s_waitcnt vmcnt(6)
	ds_write_b128 v110, v[138:141]
	ds_write_b128 v110, v[142:145] offset:4096
	ds_write_b128 v110, v[154:157] offset:16384
	ds_write_b128 v110, v[158:161] offset:20480
	ds_write_b128 v110, v[162:165] offset:24576
	ds_write_b128 v110, v[166:169] offset:28672
	global_load_dwordx4 v[138:141], v79, s[98:99] offset:256
	global_load_dwordx4 v[142:145], v80, s[98:99] offset:256
	global_load_dwordx4 v[154:157], v93, s[100:101] offset:256
	global_load_dwordx4 v[158:161], v94, s[100:101] offset:256
	global_load_dwordx4 v[162:165], v95, s[100:101] offset:256
	global_load_dwordx4 v[166:169], v109, s[100:101] offset:256
	s_waitcnt lgkmcnt(0)
	s_barrier
	ds_read_b128 v[32:35], v239
	ds_read_b128 v[40:43], v241
	ds_read_b128 v[44:47], v241 offset:2048
	ds_read_b128 v[48:51], v241 offset:4096
	ds_read_b128 v[52:55], v241 offset:6144
	ds_read_b128 v[36:39], v239 offset:2048
	s_waitcnt lgkmcnt(4)
	v_mfma_f32_16x16x32_bf16 v[0:3], v[32:35], v[40:43], 0
	ds_read_b128 v[56:59], v240
	s_waitcnt lgkmcnt(4)
	v_mfma_f32_16x16x32_bf16 v[4:7], v[32:35], v[44:47], 0
	ds_read_b128 v[118:121], v242
	s_waitcnt lgkmcnt(4)
	v_mfma_f32_16x16x32_bf16 v[8:11], v[32:35], v[48:51], 0
	ds_read_b128 v[126:129], v242 offset:2048
	s_waitcnt lgkmcnt(4)
	v_mfma_f32_16x16x32_bf16 v[12:15], v[32:35], v[52:55], 0
	ds_read_b128 v[130:133], v242 offset:4096
	s_waitcnt lgkmcnt(4)
	v_mfma_f32_16x16x32_bf16 v[16:19], v[36:39], v[40:43], 0
	ds_read_b128 v[134:137], v242 offset:6144
	v_mfma_f32_16x16x32_bf16 v[20:23], v[36:39], v[44:47], 0
	ds_read_b128 v[60:63], v240 offset:2048
	v_mfma_f32_16x16x32_bf16 v[24:27], v[36:39], v[48:51], 0
	v_mfma_f32_16x16x32_bf16 v[28:31], v[36:39], v[52:55], 0
	s_waitcnt lgkmcnt(4)
	v_mfma_f32_16x16x32_bf16 v[0:3], v[56:59], v[118:121], v[0:3]
	s_waitcnt vmcnt(6)
	ds_write_b128 v110, v[170:173] offset:32768
	s_waitcnt lgkmcnt(4)
	v_mfma_f32_16x16x32_bf16 v[4:7], v[56:59], v[126:129], v[4:7]
	ds_write_b128 v110, v[174:177] offset:36864
	s_waitcnt lgkmcnt(4)
	v_mfma_f32_16x16x32_bf16 v[8:11], v[56:59], v[130:133], v[8:11]
	ds_write_b128 v110, v[178:181] offset:49152
	global_load_dwordx4 v[170:173], v79, s[98:99] offset:384
	s_waitcnt lgkmcnt(4)
	v_mfma_f32_16x16x32_bf16 v[12:15], v[56:59], v[134:137], v[12:15]
	ds_write_b128 v110, v[182:185] offset:53248
	global_load_dwordx4 v[174:177], v80, s[98:99] offset:384
	s_waitcnt lgkmcnt(4)
	v_mfma_f32_16x16x32_bf16 v[16:19], v[60:63], v[118:121], v[16:19]
	ds_write_b128 v110, v[186:189] offset:57344
	global_load_dwordx4 v[178:181], v93, s[100:101] offset:384
	v_mfma_f32_16x16x32_bf16 v[20:23], v[60:63], v[126:129], v[20:23]
	ds_write_b128 v110, v[190:193] offset:61440
	global_load_dwordx4 v[182:185], v94, s[100:101] offset:384
	v_mfma_f32_16x16x32_bf16 v[24:27], v[60:63], v[130:133], v[24:27]
	global_load_dwordx4 v[186:189], v95, s[100:101] offset:384
	v_mfma_f32_16x16x32_bf16 v[28:31], v[60:63], v[134:137], v[28:31]
	global_load_dwordx4 v[190:193], v109, s[100:101] offset:384
	s_waitcnt lgkmcnt(0)
	s_barrier
	ds_read_b128 v[32:35], v239 offset:32768
	ds_read_b128 v[40:43], v241 offset:32768
	ds_read_b128 v[44:47], v241 offset:34816
	ds_read_b128 v[48:51], v241 offset:36864
	ds_read_b128 v[52:55], v241 offset:38912
	ds_read_b128 v[36:39], v239 offset:34816
	s_waitcnt lgkmcnt(4)
	v_mfma_f32_16x16x32_bf16 v[0:3], v[32:35], v[40:43], v[0:3]
	ds_read_b128 v[56:59], v240 offset:32768
	s_waitcnt lgkmcnt(4)
	v_mfma_f32_16x16x32_bf16 v[4:7], v[32:35], v[44:47], v[4:7]
	ds_read_b128 v[118:121], v242 offset:32768
	s_waitcnt lgkmcnt(4)
	v_mfma_f32_16x16x32_bf16 v[8:11], v[32:35], v[48:51], v[8:11]
	ds_read_b128 v[126:129], v242 offset:34816
	s_waitcnt lgkmcnt(4)
	v_mfma_f32_16x16x32_bf16 v[12:15], v[32:35], v[52:55], v[12:15]
	ds_read_b128 v[130:133], v242 offset:36864
	s_waitcnt lgkmcnt(4)
	v_mfma_f32_16x16x32_bf16 v[16:19], v[36:39], v[40:43], v[16:19]
	ds_read_b128 v[134:137], v242 offset:38912
	v_mfma_f32_16x16x32_bf16 v[20:23], v[36:39], v[44:47], v[20:23]
	ds_read_b128 v[60:63], v240 offset:34816
	v_mfma_f32_16x16x32_bf16 v[24:27], v[36:39], v[48:51], v[24:27]
	v_mfma_f32_16x16x32_bf16 v[28:31], v[36:39], v[52:55], v[28:31]
	s_waitcnt lgkmcnt(4)
	v_mfma_f32_16x16x32_bf16 v[0:3], v[56:59], v[118:121], v[0:3]
	s_waitcnt vmcnt(6)
	ds_write_b128 v110, v[138:141]
	s_waitcnt lgkmcnt(4)
	v_mfma_f32_16x16x32_bf16 v[4:7], v[56:59], v[126:129], v[4:7]
	ds_write_b128 v110, v[142:145] offset:4096
	s_waitcnt lgkmcnt(4)
	v_mfma_f32_16x16x32_bf16 v[8:11], v[56:59], v[130:133], v[8:11]
	ds_write_b128 v110, v[154:157] offset:16384
	global_load_dwordx4 v[138:141], v79, s[98:99] offset:512
	s_waitcnt lgkmcnt(4)
	v_mfma_f32_16x16x32_bf16 v[12:15], v[56:59], v[134:137], v[12:15]
	ds_write_b128 v110, v[158:161] offset:20480
	global_load_dwordx4 v[142:145], v80, s[98:99] offset:512
	s_waitcnt lgkmcnt(4)
	v_mfma_f32_16x16x32_bf16 v[16:19], v[60:63], v[118:121], v[16:19]
	ds_write_b128 v110, v[162:165] offset:24576
	global_load_dwordx4 v[154:157], v93, s[100:101] offset:512
	v_mfma_f32_16x16x32_bf16 v[20:23], v[60:63], v[126:129], v[20:23]
	ds_write_b128 v110, v[166:169] offset:28672
	global_load_dwordx4 v[158:161], v94, s[100:101] offset:512
	v_mfma_f32_16x16x32_bf16 v[24:27], v[60:63], v[130:133], v[24:27]
	global_load_dwordx4 v[162:165], v95, s[100:101] offset:512
	v_mfma_f32_16x16x32_bf16 v[28:31], v[60:63], v[134:137], v[28:31]
	global_load_dwordx4 v[166:169], v109, s[100:101] offset:512
	s_waitcnt lgkmcnt(0)
	s_barrier
	ds_read_b128 v[32:35], v239
	ds_read_b128 v[40:43], v241
	ds_read_b128 v[44:47], v241 offset:2048
	ds_read_b128 v[48:51], v241 offset:4096
	ds_read_b128 v[52:55], v241 offset:6144
	ds_read_b128 v[36:39], v239 offset:2048
	s_waitcnt lgkmcnt(4)
	v_mfma_f32_16x16x32_bf16 v[0:3], v[32:35], v[40:43], v[0:3]
	ds_read_b128 v[56:59], v240
	s_waitcnt lgkmcnt(4)
	v_mfma_f32_16x16x32_bf16 v[4:7], v[32:35], v[44:47], v[4:7]
	ds_read_b128 v[118:121], v242
	s_waitcnt lgkmcnt(4)
	v_mfma_f32_16x16x32_bf16 v[8:11], v[32:35], v[48:51], v[8:11]
	ds_read_b128 v[126:129], v242 offset:2048
	s_waitcnt lgkmcnt(4)
	v_mfma_f32_16x16x32_bf16 v[12:15], v[32:35], v[52:55], v[12:15]
	ds_read_b128 v[130:133], v242 offset:4096
	s_waitcnt lgkmcnt(4)
	v_mfma_f32_16x16x32_bf16 v[16:19], v[36:39], v[40:43], v[16:19]
	ds_read_b128 v[134:137], v242 offset:6144
	v_mfma_f32_16x16x32_bf16 v[20:23], v[36:39], v[44:47], v[20:23]
	ds_read_b128 v[60:63], v240 offset:2048
	v_mfma_f32_16x16x32_bf16 v[24:27], v[36:39], v[48:51], v[24:27]
	v_mfma_f32_16x16x32_bf16 v[28:31], v[36:39], v[52:55], v[28:31]
	s_waitcnt lgkmcnt(4)
	v_mfma_f32_16x16x32_bf16 v[0:3], v[56:59], v[118:121], v[0:3]
	s_waitcnt vmcnt(6)
	ds_write_b128 v110, v[170:173] offset:32768
	s_waitcnt lgkmcnt(4)
	v_mfma_f32_16x16x32_bf16 v[4:7], v[56:59], v[126:129], v[4:7]
	ds_write_b128 v110, v[174:177] offset:36864
	s_waitcnt lgkmcnt(4)
	v_mfma_f32_16x16x32_bf16 v[8:11], v[56:59], v[130:133], v[8:11]
	ds_write_b128 v110, v[178:181] offset:49152
	global_load_dwordx4 v[170:173], v79, s[98:99] offset:640
	s_waitcnt lgkmcnt(4)
	v_mfma_f32_16x16x32_bf16 v[12:15], v[56:59], v[134:137], v[12:15]
	ds_write_b128 v110, v[182:185] offset:53248
	global_load_dwordx4 v[174:177], v80, s[98:99] offset:640
	s_waitcnt lgkmcnt(4)
	v_mfma_f32_16x16x32_bf16 v[16:19], v[60:63], v[118:121], v[16:19]
	ds_write_b128 v110, v[186:189] offset:57344
	global_load_dwordx4 v[178:181], v93, s[100:101] offset:640
	v_mfma_f32_16x16x32_bf16 v[20:23], v[60:63], v[126:129], v[20:23]
	ds_write_b128 v110, v[190:193] offset:61440
	global_load_dwordx4 v[182:185], v94, s[100:101] offset:640
	v_mfma_f32_16x16x32_bf16 v[24:27], v[60:63], v[130:133], v[24:27]
	global_load_dwordx4 v[186:189], v95, s[100:101] offset:640
	v_mfma_f32_16x16x32_bf16 v[28:31], v[60:63], v[134:137], v[28:31]
	global_load_dwordx4 v[190:193], v109, s[100:101] offset:640
	s_waitcnt lgkmcnt(0)
	s_barrier
	ds_read_b128 v[32:35], v239 offset:32768
	ds_read_b128 v[40:43], v241 offset:32768
	ds_read_b128 v[44:47], v241 offset:34816
	ds_read_b128 v[48:51], v241 offset:36864
	ds_read_b128 v[52:55], v241 offset:38912
	ds_read_b128 v[36:39], v239 offset:34816
	s_waitcnt lgkmcnt(4)
	v_mfma_f32_16x16x32_bf16 v[0:3], v[32:35], v[40:43], v[0:3]
	ds_read_b128 v[56:59], v240 offset:32768
	s_waitcnt lgkmcnt(4)
	v_mfma_f32_16x16x32_bf16 v[4:7], v[32:35], v[44:47], v[4:7]
	ds_read_b128 v[118:121], v242 offset:32768
	s_waitcnt lgkmcnt(4)
	v_mfma_f32_16x16x32_bf16 v[8:11], v[32:35], v[48:51], v[8:11]
	ds_read_b128 v[126:129], v242 offset:34816
	s_waitcnt lgkmcnt(4)
	v_mfma_f32_16x16x32_bf16 v[12:15], v[32:35], v[52:55], v[12:15]
	ds_read_b128 v[130:133], v242 offset:36864
	s_waitcnt lgkmcnt(4)
	v_mfma_f32_16x16x32_bf16 v[16:19], v[36:39], v[40:43], v[16:19]
	ds_read_b128 v[134:137], v242 offset:38912
	v_mfma_f32_16x16x32_bf16 v[20:23], v[36:39], v[44:47], v[20:23]
	ds_read_b128 v[60:63], v240 offset:34816
	v_mfma_f32_16x16x32_bf16 v[24:27], v[36:39], v[48:51], v[24:27]
	v_mfma_f32_16x16x32_bf16 v[28:31], v[36:39], v[52:55], v[28:31]
	s_waitcnt lgkmcnt(4)
	v_mfma_f32_16x16x32_bf16 v[0:3], v[56:59], v[118:121], v[0:3]
	s_waitcnt vmcnt(6)
	ds_write_b128 v110, v[138:141]
	s_waitcnt lgkmcnt(4)
	v_mfma_f32_16x16x32_bf16 v[4:7], v[56:59], v[126:129], v[4:7]
	ds_write_b128 v110, v[142:145] offset:4096
	s_waitcnt lgkmcnt(4)
	v_mfma_f32_16x16x32_bf16 v[8:11], v[56:59], v[130:133], v[8:11]
	ds_write_b128 v110, v[154:157] offset:16384
	global_load_dwordx4 v[138:141], v79, s[98:99] offset:768
	s_waitcnt lgkmcnt(4)
	v_mfma_f32_16x16x32_bf16 v[12:15], v[56:59], v[134:137], v[12:15]
	ds_write_b128 v110, v[158:161] offset:20480
	global_load_dwordx4 v[142:145], v80, s[98:99] offset:768
	s_waitcnt lgkmcnt(4)
	v_mfma_f32_16x16x32_bf16 v[16:19], v[60:63], v[118:121], v[16:19]
	ds_write_b128 v110, v[162:165] offset:24576
	global_load_dwordx4 v[154:157], v93, s[100:101] offset:768
	v_mfma_f32_16x16x32_bf16 v[20:23], v[60:63], v[126:129], v[20:23]
	ds_write_b128 v110, v[166:169] offset:28672
	global_load_dwordx4 v[158:161], v94, s[100:101] offset:768
	v_mfma_f32_16x16x32_bf16 v[24:27], v[60:63], v[130:133], v[24:27]
	global_load_dwordx4 v[162:165], v95, s[100:101] offset:768
	v_mfma_f32_16x16x32_bf16 v[28:31], v[60:63], v[134:137], v[28:31]
	global_load_dwordx4 v[166:169], v109, s[100:101] offset:768
	s_waitcnt lgkmcnt(0)
	s_barrier
	ds_read_b128 v[32:35], v239
	ds_read_b128 v[40:43], v241
	ds_read_b128 v[44:47], v241 offset:2048
	ds_read_b128 v[48:51], v241 offset:4096
	ds_read_b128 v[52:55], v241 offset:6144
	ds_read_b128 v[36:39], v239 offset:2048
	s_waitcnt lgkmcnt(4)
	v_mfma_f32_16x16x32_bf16 v[0:3], v[32:35], v[40:43], v[0:3]
	ds_read_b128 v[56:59], v240
	s_waitcnt lgkmcnt(4)
	v_mfma_f32_16x16x32_bf16 v[4:7], v[32:35], v[44:47], v[4:7]
	ds_read_b128 v[118:121], v242
	s_waitcnt lgkmcnt(4)
	v_mfma_f32_16x16x32_bf16 v[8:11], v[32:35], v[48:51], v[8:11]
	ds_read_b128 v[126:129], v242 offset:2048
	s_waitcnt lgkmcnt(4)
	v_mfma_f32_16x16x32_bf16 v[12:15], v[32:35], v[52:55], v[12:15]
	ds_read_b128 v[130:133], v242 offset:4096
	s_waitcnt lgkmcnt(4)
	v_mfma_f32_16x16x32_bf16 v[16:19], v[36:39], v[40:43], v[16:19]
	ds_read_b128 v[134:137], v242 offset:6144
	v_mfma_f32_16x16x32_bf16 v[20:23], v[36:39], v[44:47], v[20:23]
	ds_read_b128 v[60:63], v240 offset:2048
	v_mfma_f32_16x16x32_bf16 v[24:27], v[36:39], v[48:51], v[24:27]
	v_mfma_f32_16x16x32_bf16 v[28:31], v[36:39], v[52:55], v[28:31]
	s_waitcnt lgkmcnt(4)
	v_mfma_f32_16x16x32_bf16 v[0:3], v[56:59], v[118:121], v[0:3]
	s_waitcnt vmcnt(6)
	ds_write_b128 v110, v[170:173] offset:32768
	s_waitcnt lgkmcnt(4)
	v_mfma_f32_16x16x32_bf16 v[4:7], v[56:59], v[126:129], v[4:7]
	ds_write_b128 v110, v[174:177] offset:36864
	s_waitcnt lgkmcnt(4)
	v_mfma_f32_16x16x32_bf16 v[8:11], v[56:59], v[130:133], v[8:11]
	ds_write_b128 v110, v[178:181] offset:49152
	global_load_dwordx4 v[170:173], v79, s[98:99] offset:896
	s_waitcnt lgkmcnt(4)
	v_mfma_f32_16x16x32_bf16 v[12:15], v[56:59], v[134:137], v[12:15]
	ds_write_b128 v110, v[182:185] offset:53248
	global_load_dwordx4 v[174:177], v80, s[98:99] offset:896
	s_waitcnt lgkmcnt(4)
	v_mfma_f32_16x16x32_bf16 v[16:19], v[60:63], v[118:121], v[16:19]
	ds_write_b128 v110, v[186:189] offset:57344
	global_load_dwordx4 v[178:181], v93, s[100:101] offset:896
	v_mfma_f32_16x16x32_bf16 v[20:23], v[60:63], v[126:129], v[20:23]
	ds_write_b128 v110, v[190:193] offset:61440
	global_load_dwordx4 v[182:185], v94, s[100:101] offset:896
	v_mfma_f32_16x16x32_bf16 v[24:27], v[60:63], v[130:133], v[24:27]
	global_load_dwordx4 v[186:189], v95, s[100:101] offset:896
	v_mfma_f32_16x16x32_bf16 v[28:31], v[60:63], v[134:137], v[28:31]
	global_load_dwordx4 v[190:193], v109, s[100:101] offset:896
	s_waitcnt lgkmcnt(0)
	s_barrier
	ds_read_b128 v[32:35], v239 offset:32768
	ds_read_b128 v[40:43], v241 offset:32768
	ds_read_b128 v[44:47], v241 offset:34816
	ds_read_b128 v[48:51], v241 offset:36864
	ds_read_b128 v[52:55], v241 offset:38912
	ds_read_b128 v[36:39], v239 offset:34816
	s_waitcnt lgkmcnt(4)
	v_mfma_f32_16x16x32_bf16 v[0:3], v[32:35], v[40:43], v[0:3]
	ds_read_b128 v[56:59], v240 offset:32768
	s_waitcnt lgkmcnt(4)
	v_mfma_f32_16x16x32_bf16 v[4:7], v[32:35], v[44:47], v[4:7]
	ds_read_b128 v[118:121], v242 offset:32768
	s_waitcnt lgkmcnt(4)
	v_mfma_f32_16x16x32_bf16 v[8:11], v[32:35], v[48:51], v[8:11]
	ds_read_b128 v[126:129], v242 offset:34816
	s_waitcnt lgkmcnt(4)
	v_mfma_f32_16x16x32_bf16 v[12:15], v[32:35], v[52:55], v[12:15]
	ds_read_b128 v[130:133], v242 offset:36864
	s_waitcnt lgkmcnt(4)
	v_mfma_f32_16x16x32_bf16 v[16:19], v[36:39], v[40:43], v[16:19]
	ds_read_b128 v[134:137], v242 offset:38912
	v_mfma_f32_16x16x32_bf16 v[20:23], v[36:39], v[44:47], v[20:23]
	ds_read_b128 v[60:63], v240 offset:34816
	v_mfma_f32_16x16x32_bf16 v[24:27], v[36:39], v[48:51], v[24:27]
	v_mfma_f32_16x16x32_bf16 v[28:31], v[36:39], v[52:55], v[28:31]
	s_waitcnt lgkmcnt(4)
	v_mfma_f32_16x16x32_bf16 v[0:3], v[56:59], v[118:121], v[0:3]
	s_waitcnt vmcnt(6)
	ds_write_b128 v110, v[138:141]
	s_waitcnt lgkmcnt(4)
	v_mfma_f32_16x16x32_bf16 v[4:7], v[56:59], v[126:129], v[4:7]
	ds_write_b128 v110, v[142:145] offset:4096
	s_waitcnt lgkmcnt(4)
	v_mfma_f32_16x16x32_bf16 v[8:11], v[56:59], v[130:133], v[8:11]
	ds_write_b128 v110, v[154:157] offset:16384
	global_load_dwordx4 v[138:141], v79, s[98:99] offset:1024
	s_waitcnt lgkmcnt(4)
	v_mfma_f32_16x16x32_bf16 v[12:15], v[56:59], v[134:137], v[12:15]
	ds_write_b128 v110, v[158:161] offset:20480
	global_load_dwordx4 v[142:145], v80, s[98:99] offset:1024
	s_waitcnt lgkmcnt(4)
	v_mfma_f32_16x16x32_bf16 v[16:19], v[60:63], v[118:121], v[16:19]
	ds_write_b128 v110, v[162:165] offset:24576
	global_load_dwordx4 v[154:157], v93, s[100:101] offset:1024
	v_mfma_f32_16x16x32_bf16 v[20:23], v[60:63], v[126:129], v[20:23]
	ds_write_b128 v110, v[166:169] offset:28672
	global_load_dwordx4 v[158:161], v94, s[100:101] offset:1024
	v_mfma_f32_16x16x32_bf16 v[24:27], v[60:63], v[130:133], v[24:27]
	global_load_dwordx4 v[162:165], v95, s[100:101] offset:1024
	v_mfma_f32_16x16x32_bf16 v[28:31], v[60:63], v[134:137], v[28:31]
	global_load_dwordx4 v[166:169], v109, s[100:101] offset:1024
	s_waitcnt lgkmcnt(0)
	s_barrier
	ds_read_b128 v[32:35], v239
	ds_read_b128 v[40:43], v241
	ds_read_b128 v[44:47], v241 offset:2048
	ds_read_b128 v[48:51], v241 offset:4096
	ds_read_b128 v[52:55], v241 offset:6144
	ds_read_b128 v[36:39], v239 offset:2048
	s_waitcnt lgkmcnt(4)
	v_mfma_f32_16x16x32_bf16 v[0:3], v[32:35], v[40:43], v[0:3]
	ds_read_b128 v[56:59], v240
	s_waitcnt lgkmcnt(4)
	v_mfma_f32_16x16x32_bf16 v[4:7], v[32:35], v[44:47], v[4:7]
	ds_read_b128 v[118:121], v242
	s_waitcnt lgkmcnt(4)
	v_mfma_f32_16x16x32_bf16 v[8:11], v[32:35], v[48:51], v[8:11]
	ds_read_b128 v[126:129], v242 offset:2048
	s_waitcnt lgkmcnt(4)
	v_mfma_f32_16x16x32_bf16 v[12:15], v[32:35], v[52:55], v[12:15]
	ds_read_b128 v[130:133], v242 offset:4096
	s_waitcnt lgkmcnt(4)
	v_mfma_f32_16x16x32_bf16 v[16:19], v[36:39], v[40:43], v[16:19]
	ds_read_b128 v[134:137], v242 offset:6144
	v_mfma_f32_16x16x32_bf16 v[20:23], v[36:39], v[44:47], v[20:23]
	ds_read_b128 v[60:63], v240 offset:2048
	v_mfma_f32_16x16x32_bf16 v[24:27], v[36:39], v[48:51], v[24:27]
	v_mfma_f32_16x16x32_bf16 v[28:31], v[36:39], v[52:55], v[28:31]
	s_waitcnt lgkmcnt(4)
	v_mfma_f32_16x16x32_bf16 v[0:3], v[56:59], v[118:121], v[0:3]
	s_waitcnt vmcnt(6)
	ds_write_b128 v110, v[170:173] offset:32768
	s_waitcnt lgkmcnt(4)
	v_mfma_f32_16x16x32_bf16 v[4:7], v[56:59], v[126:129], v[4:7]
	ds_write_b128 v110, v[174:177] offset:36864
	s_waitcnt lgkmcnt(4)
	v_mfma_f32_16x16x32_bf16 v[8:11], v[56:59], v[130:133], v[8:11]
	ds_write_b128 v110, v[178:181] offset:49152
	global_load_dwordx4 v[170:173], v79, s[98:99] offset:1152
	s_waitcnt lgkmcnt(4)
	v_mfma_f32_16x16x32_bf16 v[12:15], v[56:59], v[134:137], v[12:15]
	ds_write_b128 v110, v[182:185] offset:53248
	global_load_dwordx4 v[174:177], v80, s[98:99] offset:1152
	s_waitcnt lgkmcnt(4)
	v_mfma_f32_16x16x32_bf16 v[16:19], v[60:63], v[118:121], v[16:19]
	ds_write_b128 v110, v[186:189] offset:57344
	global_load_dwordx4 v[178:181], v93, s[100:101] offset:1152
	v_mfma_f32_16x16x32_bf16 v[20:23], v[60:63], v[126:129], v[20:23]
	ds_write_b128 v110, v[190:193] offset:61440
	global_load_dwordx4 v[182:185], v94, s[100:101] offset:1152
	v_mfma_f32_16x16x32_bf16 v[24:27], v[60:63], v[130:133], v[24:27]
	global_load_dwordx4 v[186:189], v95, s[100:101] offset:1152
	v_mfma_f32_16x16x32_bf16 v[28:31], v[60:63], v[134:137], v[28:31]
	global_load_dwordx4 v[190:193], v109, s[100:101] offset:1152
	s_waitcnt lgkmcnt(0)
	s_barrier
	ds_read_b128 v[32:35], v239 offset:32768
	ds_read_b128 v[40:43], v241 offset:32768
	ds_read_b128 v[44:47], v241 offset:34816
	ds_read_b128 v[48:51], v241 offset:36864
	ds_read_b128 v[52:55], v241 offset:38912
	ds_read_b128 v[36:39], v239 offset:34816
	s_waitcnt lgkmcnt(4)
	v_mfma_f32_16x16x32_bf16 v[0:3], v[32:35], v[40:43], v[0:3]
	ds_read_b128 v[56:59], v240 offset:32768
	s_waitcnt lgkmcnt(4)
	v_mfma_f32_16x16x32_bf16 v[4:7], v[32:35], v[44:47], v[4:7]
	ds_read_b128 v[118:121], v242 offset:32768
	s_waitcnt lgkmcnt(4)
	v_mfma_f32_16x16x32_bf16 v[8:11], v[32:35], v[48:51], v[8:11]
	ds_read_b128 v[126:129], v242 offset:34816
	s_waitcnt lgkmcnt(4)
	v_mfma_f32_16x16x32_bf16 v[12:15], v[32:35], v[52:55], v[12:15]
	ds_read_b128 v[130:133], v242 offset:36864
	s_waitcnt lgkmcnt(4)
	v_mfma_f32_16x16x32_bf16 v[16:19], v[36:39], v[40:43], v[16:19]
	ds_read_b128 v[134:137], v242 offset:38912
	v_mfma_f32_16x16x32_bf16 v[20:23], v[36:39], v[44:47], v[20:23]
	ds_read_b128 v[60:63], v240 offset:34816
	v_mfma_f32_16x16x32_bf16 v[24:27], v[36:39], v[48:51], v[24:27]
	v_mfma_f32_16x16x32_bf16 v[28:31], v[36:39], v[52:55], v[28:31]
	s_waitcnt lgkmcnt(4)
	v_mfma_f32_16x16x32_bf16 v[0:3], v[56:59], v[118:121], v[0:3]
	s_waitcnt vmcnt(6)
	ds_write_b128 v110, v[138:141]
	s_waitcnt lgkmcnt(4)
	v_mfma_f32_16x16x32_bf16 v[4:7], v[56:59], v[126:129], v[4:7]
	ds_write_b128 v110, v[142:145] offset:4096
	s_waitcnt lgkmcnt(4)
	v_mfma_f32_16x16x32_bf16 v[8:11], v[56:59], v[130:133], v[8:11]
	ds_write_b128 v110, v[154:157] offset:16384
	global_load_dwordx4 v[138:141], v79, s[98:99] offset:1280
	s_waitcnt lgkmcnt(4)
	v_mfma_f32_16x16x32_bf16 v[12:15], v[56:59], v[134:137], v[12:15]
	ds_write_b128 v110, v[158:161] offset:20480
	global_load_dwordx4 v[142:145], v80, s[98:99] offset:1280
	s_waitcnt lgkmcnt(4)
	v_mfma_f32_16x16x32_bf16 v[16:19], v[60:63], v[118:121], v[16:19]
	ds_write_b128 v110, v[162:165] offset:24576
	global_load_dwordx4 v[154:157], v93, s[100:101] offset:1280
	v_mfma_f32_16x16x32_bf16 v[20:23], v[60:63], v[126:129], v[20:23]
	ds_write_b128 v110, v[166:169] offset:28672
	global_load_dwordx4 v[158:161], v94, s[100:101] offset:1280
	v_mfma_f32_16x16x32_bf16 v[24:27], v[60:63], v[130:133], v[24:27]
	global_load_dwordx4 v[162:165], v95, s[100:101] offset:1280
	v_mfma_f32_16x16x32_bf16 v[28:31], v[60:63], v[134:137], v[28:31]
	global_load_dwordx4 v[166:169], v109, s[100:101] offset:1280
	s_waitcnt lgkmcnt(0)
	s_barrier
	ds_read_b128 v[32:35], v239
	ds_read_b128 v[40:43], v241
	ds_read_b128 v[44:47], v241 offset:2048
	ds_read_b128 v[48:51], v241 offset:4096
	ds_read_b128 v[52:55], v241 offset:6144
	ds_read_b128 v[36:39], v239 offset:2048
	s_waitcnt lgkmcnt(4)
	v_mfma_f32_16x16x32_bf16 v[0:3], v[32:35], v[40:43], v[0:3]
	ds_read_b128 v[56:59], v240
	s_waitcnt lgkmcnt(4)
	v_mfma_f32_16x16x32_bf16 v[4:7], v[32:35], v[44:47], v[4:7]
	ds_read_b128 v[118:121], v242
	s_waitcnt lgkmcnt(4)
	v_mfma_f32_16x16x32_bf16 v[8:11], v[32:35], v[48:51], v[8:11]
	ds_read_b128 v[126:129], v242 offset:2048
	s_waitcnt lgkmcnt(4)
	v_mfma_f32_16x16x32_bf16 v[12:15], v[32:35], v[52:55], v[12:15]
	ds_read_b128 v[130:133], v242 offset:4096
	s_waitcnt lgkmcnt(4)
	v_mfma_f32_16x16x32_bf16 v[16:19], v[36:39], v[40:43], v[16:19]
	ds_read_b128 v[134:137], v242 offset:6144
	v_mfma_f32_16x16x32_bf16 v[20:23], v[36:39], v[44:47], v[20:23]
	ds_read_b128 v[60:63], v240 offset:2048
	v_mfma_f32_16x16x32_bf16 v[24:27], v[36:39], v[48:51], v[24:27]
	v_mfma_f32_16x16x32_bf16 v[28:31], v[36:39], v[52:55], v[28:31]
	s_waitcnt lgkmcnt(4)
	v_mfma_f32_16x16x32_bf16 v[0:3], v[56:59], v[118:121], v[0:3]
	s_waitcnt vmcnt(6)
	ds_write_b128 v110, v[170:173] offset:32768
	s_waitcnt lgkmcnt(4)
	v_mfma_f32_16x16x32_bf16 v[4:7], v[56:59], v[126:129], v[4:7]
	ds_write_b128 v110, v[174:177] offset:36864
	s_waitcnt lgkmcnt(4)
	v_mfma_f32_16x16x32_bf16 v[8:11], v[56:59], v[130:133], v[8:11]
	ds_write_b128 v110, v[178:181] offset:49152
	global_load_dwordx4 v[170:173], v79, s[98:99] offset:1408
	s_waitcnt lgkmcnt(4)
	v_mfma_f32_16x16x32_bf16 v[12:15], v[56:59], v[134:137], v[12:15]
	ds_write_b128 v110, v[182:185] offset:53248
	global_load_dwordx4 v[174:177], v80, s[98:99] offset:1408
	s_waitcnt lgkmcnt(4)
	v_mfma_f32_16x16x32_bf16 v[16:19], v[60:63], v[118:121], v[16:19]
	ds_write_b128 v110, v[186:189] offset:57344
	global_load_dwordx4 v[178:181], v93, s[100:101] offset:1408
	v_mfma_f32_16x16x32_bf16 v[20:23], v[60:63], v[126:129], v[20:23]
	ds_write_b128 v110, v[190:193] offset:61440
	global_load_dwordx4 v[182:185], v94, s[100:101] offset:1408
	v_mfma_f32_16x16x32_bf16 v[24:27], v[60:63], v[130:133], v[24:27]
	global_load_dwordx4 v[186:189], v95, s[100:101] offset:1408
	v_mfma_f32_16x16x32_bf16 v[28:31], v[60:63], v[134:137], v[28:31]
	global_load_dwordx4 v[190:193], v109, s[100:101] offset:1408
	s_waitcnt lgkmcnt(0)
	s_barrier
	ds_read_b128 v[32:35], v239 offset:32768
	ds_read_b128 v[40:43], v241 offset:32768
	ds_read_b128 v[44:47], v241 offset:34816
	ds_read_b128 v[48:51], v241 offset:36864
	ds_read_b128 v[52:55], v241 offset:38912
	ds_read_b128 v[36:39], v239 offset:34816
	s_waitcnt lgkmcnt(4)
	v_mfma_f32_16x16x32_bf16 v[0:3], v[32:35], v[40:43], v[0:3]
	ds_read_b128 v[56:59], v240 offset:32768
	s_waitcnt lgkmcnt(4)
	v_mfma_f32_16x16x32_bf16 v[4:7], v[32:35], v[44:47], v[4:7]
	ds_read_b128 v[118:121], v242 offset:32768
	s_waitcnt lgkmcnt(4)
	v_mfma_f32_16x16x32_bf16 v[8:11], v[32:35], v[48:51], v[8:11]
	ds_read_b128 v[126:129], v242 offset:34816
	s_waitcnt lgkmcnt(4)
	v_mfma_f32_16x16x32_bf16 v[12:15], v[32:35], v[52:55], v[12:15]
	ds_read_b128 v[130:133], v242 offset:36864
	s_waitcnt lgkmcnt(4)
	v_mfma_f32_16x16x32_bf16 v[16:19], v[36:39], v[40:43], v[16:19]
	ds_read_b128 v[134:137], v242 offset:38912
	v_mfma_f32_16x16x32_bf16 v[20:23], v[36:39], v[44:47], v[20:23]
	ds_read_b128 v[60:63], v240 offset:34816
	v_mfma_f32_16x16x32_bf16 v[24:27], v[36:39], v[48:51], v[24:27]
	v_mfma_f32_16x16x32_bf16 v[28:31], v[36:39], v[52:55], v[28:31]
	s_waitcnt lgkmcnt(4)
	v_mfma_f32_16x16x32_bf16 v[0:3], v[56:59], v[118:121], v[0:3]
	s_waitcnt vmcnt(6)
	ds_write_b128 v110, v[138:141]
	s_waitcnt lgkmcnt(4)
	v_mfma_f32_16x16x32_bf16 v[4:7], v[56:59], v[126:129], v[4:7]
	ds_write_b128 v110, v[142:145] offset:4096
	s_waitcnt lgkmcnt(4)
	v_mfma_f32_16x16x32_bf16 v[8:11], v[56:59], v[130:133], v[8:11]
	ds_write_b128 v110, v[154:157] offset:16384
	global_load_dwordx4 v[138:141], v79, s[98:99] offset:1536
	s_waitcnt lgkmcnt(4)
	v_mfma_f32_16x16x32_bf16 v[12:15], v[56:59], v[134:137], v[12:15]
	ds_write_b128 v110, v[158:161] offset:20480
	global_load_dwordx4 v[142:145], v80, s[98:99] offset:1536
	s_waitcnt lgkmcnt(4)
	v_mfma_f32_16x16x32_bf16 v[16:19], v[60:63], v[118:121], v[16:19]
	ds_write_b128 v110, v[162:165] offset:24576
	global_load_dwordx4 v[154:157], v93, s[100:101] offset:1536
	v_mfma_f32_16x16x32_bf16 v[20:23], v[60:63], v[126:129], v[20:23]
	ds_write_b128 v110, v[166:169] offset:28672
	global_load_dwordx4 v[158:161], v94, s[100:101] offset:1536
	v_mfma_f32_16x16x32_bf16 v[24:27], v[60:63], v[130:133], v[24:27]
	global_load_dwordx4 v[162:165], v95, s[100:101] offset:1536
	v_mfma_f32_16x16x32_bf16 v[28:31], v[60:63], v[134:137], v[28:31]
	global_load_dwordx4 v[166:169], v109, s[100:101] offset:1536
	s_waitcnt lgkmcnt(0)
	s_barrier
	ds_read_b128 v[32:35], v239
	ds_read_b128 v[40:43], v241
	ds_read_b128 v[44:47], v241 offset:2048
	ds_read_b128 v[48:51], v241 offset:4096
	ds_read_b128 v[52:55], v241 offset:6144
	ds_read_b128 v[36:39], v239 offset:2048
	s_waitcnt lgkmcnt(4)
	v_mfma_f32_16x16x32_bf16 v[0:3], v[32:35], v[40:43], v[0:3]
	ds_read_b128 v[56:59], v240
	s_waitcnt lgkmcnt(4)
	v_mfma_f32_16x16x32_bf16 v[4:7], v[32:35], v[44:47], v[4:7]
	ds_read_b128 v[118:121], v242
	s_waitcnt lgkmcnt(4)
	v_mfma_f32_16x16x32_bf16 v[8:11], v[32:35], v[48:51], v[8:11]
	ds_read_b128 v[126:129], v242 offset:2048
	s_waitcnt lgkmcnt(4)
	v_mfma_f32_16x16x32_bf16 v[12:15], v[32:35], v[52:55], v[12:15]
	ds_read_b128 v[130:133], v242 offset:4096
	s_waitcnt lgkmcnt(4)
	v_mfma_f32_16x16x32_bf16 v[16:19], v[36:39], v[40:43], v[16:19]
	ds_read_b128 v[134:137], v242 offset:6144
	v_mfma_f32_16x16x32_bf16 v[20:23], v[36:39], v[44:47], v[20:23]
	ds_read_b128 v[60:63], v240 offset:2048
	v_mfma_f32_16x16x32_bf16 v[24:27], v[36:39], v[48:51], v[24:27]
	v_mfma_f32_16x16x32_bf16 v[28:31], v[36:39], v[52:55], v[28:31]
	s_waitcnt lgkmcnt(4)
	v_mfma_f32_16x16x32_bf16 v[0:3], v[56:59], v[118:121], v[0:3]
	s_waitcnt vmcnt(6)
	ds_write_b128 v110, v[170:173] offset:32768
	s_waitcnt lgkmcnt(4)
	v_mfma_f32_16x16x32_bf16 v[4:7], v[56:59], v[126:129], v[4:7]
	ds_write_b128 v110, v[174:177] offset:36864
	s_waitcnt lgkmcnt(4)
	v_mfma_f32_16x16x32_bf16 v[8:11], v[56:59], v[130:133], v[8:11]
	ds_write_b128 v110, v[178:181] offset:49152
	global_load_dwordx4 v[170:173], v79, s[98:99] offset:1664
	s_waitcnt lgkmcnt(4)
	v_mfma_f32_16x16x32_bf16 v[12:15], v[56:59], v[134:137], v[12:15]
	ds_write_b128 v110, v[182:185] offset:53248
	global_load_dwordx4 v[174:177], v80, s[98:99] offset:1664
	s_waitcnt lgkmcnt(4)
	v_mfma_f32_16x16x32_bf16 v[16:19], v[60:63], v[118:121], v[16:19]
	ds_write_b128 v110, v[186:189] offset:57344
	global_load_dwordx4 v[178:181], v93, s[100:101] offset:1664
	v_mfma_f32_16x16x32_bf16 v[20:23], v[60:63], v[126:129], v[20:23]
	ds_write_b128 v110, v[190:193] offset:61440
	global_load_dwordx4 v[182:185], v94, s[100:101] offset:1664
	v_mfma_f32_16x16x32_bf16 v[24:27], v[60:63], v[130:133], v[24:27]
	global_load_dwordx4 v[186:189], v95, s[100:101] offset:1664
	v_mfma_f32_16x16x32_bf16 v[28:31], v[60:63], v[134:137], v[28:31]
	global_load_dwordx4 v[190:193], v109, s[100:101] offset:1664
	s_waitcnt lgkmcnt(0)
	s_barrier
	ds_read_b128 v[32:35], v239 offset:32768
	ds_read_b128 v[40:43], v241 offset:32768
	ds_read_b128 v[44:47], v241 offset:34816
	ds_read_b128 v[48:51], v241 offset:36864
	ds_read_b128 v[52:55], v241 offset:38912
	ds_read_b128 v[36:39], v239 offset:34816
	s_waitcnt lgkmcnt(4)
	v_mfma_f32_16x16x32_bf16 v[0:3], v[32:35], v[40:43], v[0:3]
	ds_read_b128 v[56:59], v240 offset:32768
	s_waitcnt lgkmcnt(4)
	v_mfma_f32_16x16x32_bf16 v[4:7], v[32:35], v[44:47], v[4:7]
	ds_read_b128 v[118:121], v242 offset:32768
	s_waitcnt lgkmcnt(4)
	v_mfma_f32_16x16x32_bf16 v[8:11], v[32:35], v[48:51], v[8:11]
	ds_read_b128 v[126:129], v242 offset:34816
	s_waitcnt lgkmcnt(4)
	v_mfma_f32_16x16x32_bf16 v[12:15], v[32:35], v[52:55], v[12:15]
	ds_read_b128 v[130:133], v242 offset:36864
	s_waitcnt lgkmcnt(4)
	v_mfma_f32_16x16x32_bf16 v[16:19], v[36:39], v[40:43], v[16:19]
	ds_read_b128 v[134:137], v242 offset:38912
	v_mfma_f32_16x16x32_bf16 v[20:23], v[36:39], v[44:47], v[20:23]
	ds_read_b128 v[60:63], v240 offset:34816
	v_mfma_f32_16x16x32_bf16 v[24:27], v[36:39], v[48:51], v[24:27]
	v_mfma_f32_16x16x32_bf16 v[28:31], v[36:39], v[52:55], v[28:31]
	s_waitcnt lgkmcnt(4)
	v_mfma_f32_16x16x32_bf16 v[0:3], v[56:59], v[118:121], v[0:3]
	s_waitcnt vmcnt(6)
	ds_write_b128 v110, v[138:141]
	s_waitcnt lgkmcnt(4)
	v_mfma_f32_16x16x32_bf16 v[4:7], v[56:59], v[126:129], v[4:7]
	ds_write_b128 v110, v[142:145] offset:4096
	s_waitcnt lgkmcnt(4)
	v_mfma_f32_16x16x32_bf16 v[8:11], v[56:59], v[130:133], v[8:11]
	ds_write_b128 v110, v[154:157] offset:16384
	global_load_dwordx4 v[138:141], v79, s[98:99] offset:1792
	s_waitcnt lgkmcnt(4)
	v_mfma_f32_16x16x32_bf16 v[12:15], v[56:59], v[134:137], v[12:15]
	ds_write_b128 v110, v[158:161] offset:20480
	global_load_dwordx4 v[142:145], v80, s[98:99] offset:1792
	s_waitcnt lgkmcnt(4)
	v_mfma_f32_16x16x32_bf16 v[16:19], v[60:63], v[118:121], v[16:19]
	ds_write_b128 v110, v[162:165] offset:24576
	global_load_dwordx4 v[154:157], v93, s[100:101] offset:1792
	v_mfma_f32_16x16x32_bf16 v[20:23], v[60:63], v[126:129], v[20:23]
	ds_write_b128 v110, v[166:169] offset:28672
	global_load_dwordx4 v[158:161], v94, s[100:101] offset:1792
	v_mfma_f32_16x16x32_bf16 v[24:27], v[60:63], v[130:133], v[24:27]
	global_load_dwordx4 v[162:165], v95, s[100:101] offset:1792
	v_mfma_f32_16x16x32_bf16 v[28:31], v[60:63], v[134:137], v[28:31]
	global_load_dwordx4 v[166:169], v109, s[100:101] offset:1792
	s_waitcnt lgkmcnt(0)
	s_barrier
	ds_read_b128 v[32:35], v239
	ds_read_b128 v[40:43], v241
	ds_read_b128 v[44:47], v241 offset:2048
	ds_read_b128 v[48:51], v241 offset:4096
	ds_read_b128 v[52:55], v241 offset:6144
	ds_read_b128 v[36:39], v239 offset:2048
	s_waitcnt lgkmcnt(4)
	v_mfma_f32_16x16x32_bf16 v[0:3], v[32:35], v[40:43], v[0:3]
	ds_read_b128 v[56:59], v240
	s_waitcnt lgkmcnt(4)
	v_mfma_f32_16x16x32_bf16 v[4:7], v[32:35], v[44:47], v[4:7]
	ds_read_b128 v[118:121], v242
	s_waitcnt lgkmcnt(4)
	v_mfma_f32_16x16x32_bf16 v[8:11], v[32:35], v[48:51], v[8:11]
	ds_read_b128 v[126:129], v242 offset:2048
	s_waitcnt lgkmcnt(4)
	v_mfma_f32_16x16x32_bf16 v[12:15], v[32:35], v[52:55], v[12:15]
	ds_read_b128 v[130:133], v242 offset:4096
	s_waitcnt lgkmcnt(4)
	v_mfma_f32_16x16x32_bf16 v[16:19], v[36:39], v[40:43], v[16:19]
	ds_read_b128 v[134:137], v242 offset:6144
	v_mfma_f32_16x16x32_bf16 v[20:23], v[36:39], v[44:47], v[20:23]
	ds_read_b128 v[60:63], v240 offset:2048
	v_mfma_f32_16x16x32_bf16 v[24:27], v[36:39], v[48:51], v[24:27]
	v_mfma_f32_16x16x32_bf16 v[28:31], v[36:39], v[52:55], v[28:31]
	s_waitcnt lgkmcnt(4)
	v_mfma_f32_16x16x32_bf16 v[0:3], v[56:59], v[118:121], v[0:3]
	s_waitcnt vmcnt(6)
	ds_write_b128 v110, v[170:173] offset:32768
	s_waitcnt lgkmcnt(4)
	v_mfma_f32_16x16x32_bf16 v[4:7], v[56:59], v[126:129], v[4:7]
	ds_write_b128 v110, v[174:177] offset:36864
	s_waitcnt lgkmcnt(4)
	v_mfma_f32_16x16x32_bf16 v[8:11], v[56:59], v[130:133], v[8:11]
	ds_write_b128 v110, v[178:181] offset:49152
	global_load_dwordx4 v[170:173], v79, s[98:99] offset:1920
	s_waitcnt lgkmcnt(4)
	v_mfma_f32_16x16x32_bf16 v[12:15], v[56:59], v[134:137], v[12:15]
	ds_write_b128 v110, v[182:185] offset:53248
	global_load_dwordx4 v[174:177], v80, s[98:99] offset:1920
	s_waitcnt lgkmcnt(4)
	v_mfma_f32_16x16x32_bf16 v[16:19], v[60:63], v[118:121], v[16:19]
	ds_write_b128 v110, v[186:189] offset:57344
	global_load_dwordx4 v[178:181], v93, s[100:101] offset:1920
	v_mfma_f32_16x16x32_bf16 v[20:23], v[60:63], v[126:129], v[20:23]
	ds_write_b128 v110, v[190:193] offset:61440
	global_load_dwordx4 v[182:185], v94, s[100:101] offset:1920
	v_mfma_f32_16x16x32_bf16 v[24:27], v[60:63], v[130:133], v[24:27]
	global_load_dwordx4 v[186:189], v95, s[100:101] offset:1920
	v_mfma_f32_16x16x32_bf16 v[28:31], v[60:63], v[134:137], v[28:31]
	global_load_dwordx4 v[190:193], v109, s[100:101] offset:1920
	s_waitcnt lgkmcnt(0)
	s_barrier
	ds_read_b128 v[32:35], v239 offset:32768
	ds_read_b128 v[40:43], v241 offset:32768
	ds_read_b128 v[44:47], v241 offset:34816
	ds_read_b128 v[48:51], v241 offset:36864
	ds_read_b128 v[52:55], v241 offset:38912
	ds_read_b128 v[36:39], v239 offset:34816
	s_waitcnt lgkmcnt(4)
	v_mfma_f32_16x16x32_bf16 v[0:3], v[32:35], v[40:43], v[0:3]
	ds_read_b128 v[56:59], v240 offset:32768
	s_waitcnt lgkmcnt(4)
	v_mfma_f32_16x16x32_bf16 v[4:7], v[32:35], v[44:47], v[4:7]
	ds_read_b128 v[118:121], v242 offset:32768
	s_waitcnt lgkmcnt(4)
	v_mfma_f32_16x16x32_bf16 v[8:11], v[32:35], v[48:51], v[8:11]
	ds_read_b128 v[126:129], v242 offset:34816
	s_waitcnt lgkmcnt(4)
	v_mfma_f32_16x16x32_bf16 v[12:15], v[32:35], v[52:55], v[12:15]
	ds_read_b128 v[130:133], v242 offset:36864
	s_waitcnt lgkmcnt(4)
	v_mfma_f32_16x16x32_bf16 v[16:19], v[36:39], v[40:43], v[16:19]
	ds_read_b128 v[134:137], v242 offset:38912
	v_mfma_f32_16x16x32_bf16 v[20:23], v[36:39], v[44:47], v[20:23]
	ds_read_b128 v[60:63], v240 offset:34816
	v_mfma_f32_16x16x32_bf16 v[24:27], v[36:39], v[48:51], v[24:27]
	v_mfma_f32_16x16x32_bf16 v[28:31], v[36:39], v[52:55], v[28:31]
	s_waitcnt lgkmcnt(4)
	v_mfma_f32_16x16x32_bf16 v[0:3], v[56:59], v[118:121], v[0:3]
	s_waitcnt vmcnt(6)
	ds_write_b128 v110, v[138:141]
	s_waitcnt lgkmcnt(4)
	v_mfma_f32_16x16x32_bf16 v[4:7], v[56:59], v[126:129], v[4:7]
	ds_write_b128 v110, v[142:145] offset:4096
	s_waitcnt lgkmcnt(4)
	v_mfma_f32_16x16x32_bf16 v[8:11], v[56:59], v[130:133], v[8:11]
	ds_write_b128 v110, v[154:157] offset:16384
	s_waitcnt lgkmcnt(4)
	v_mfma_f32_16x16x32_bf16 v[12:15], v[56:59], v[134:137], v[12:15]
	ds_write_b128 v110, v[158:161] offset:20480
	s_waitcnt lgkmcnt(4)
	v_mfma_f32_16x16x32_bf16 v[16:19], v[60:63], v[118:121], v[16:19]
	ds_write_b128 v110, v[162:165] offset:24576
	v_mfma_f32_16x16x32_bf16 v[20:23], v[60:63], v[126:129], v[20:23]
	ds_write_b128 v110, v[166:169] offset:28672
	v_mfma_f32_16x16x32_bf16 v[24:27], v[60:63], v[130:133], v[24:27]
	v_mfma_f32_16x16x32_bf16 v[28:31], v[60:63], v[134:137], v[28:31]
	s_waitcnt lgkmcnt(0)
	s_barrier
	ds_read_b128 v[32:35], v239
	ds_read_b128 v[40:43], v241
	ds_read_b128 v[44:47], v241 offset:2048
	ds_read_b128 v[48:51], v241 offset:4096
	ds_read_b128 v[52:55], v241 offset:6144
	ds_read_b128 v[36:39], v239 offset:2048
	s_waitcnt lgkmcnt(4)
	v_mfma_f32_16x16x32_bf16 v[0:3], v[32:35], v[40:43], v[0:3]
	ds_read_b128 v[56:59], v240
	s_waitcnt lgkmcnt(4)
	v_mfma_f32_16x16x32_bf16 v[4:7], v[32:35], v[44:47], v[4:7]
	ds_read_b128 v[118:121], v242
	s_waitcnt lgkmcnt(4)
	v_mfma_f32_16x16x32_bf16 v[8:11], v[32:35], v[48:51], v[8:11]
	ds_read_b128 v[126:129], v242 offset:2048
	s_waitcnt lgkmcnt(4)
	v_mfma_f32_16x16x32_bf16 v[12:15], v[32:35], v[52:55], v[12:15]
	ds_read_b128 v[130:133], v242 offset:4096
	s_waitcnt lgkmcnt(4)
	v_mfma_f32_16x16x32_bf16 v[16:19], v[36:39], v[40:43], v[16:19]
	ds_read_b128 v[134:137], v242 offset:6144
	v_mfma_f32_16x16x32_bf16 v[20:23], v[36:39], v[44:47], v[20:23]
	ds_read_b128 v[60:63], v240 offset:2048
	v_mfma_f32_16x16x32_bf16 v[24:27], v[36:39], v[48:51], v[24:27]
	v_mfma_f32_16x16x32_bf16 v[28:31], v[36:39], v[52:55], v[28:31]
	s_waitcnt lgkmcnt(4)
	v_mfma_f32_16x16x32_bf16 v[0:3], v[56:59], v[118:121], v[0:3]
	s_waitcnt vmcnt(0)
	ds_write_b128 v110, v[170:173] offset:32768
	s_waitcnt lgkmcnt(4)
	v_mfma_f32_16x16x32_bf16 v[4:7], v[56:59], v[126:129], v[4:7]
	ds_write_b128 v110, v[174:177] offset:36864
	s_waitcnt lgkmcnt(4)
	v_mfma_f32_16x16x32_bf16 v[8:11], v[56:59], v[130:133], v[8:11]
	ds_write_b128 v110, v[178:181] offset:49152
	s_waitcnt lgkmcnt(4)
	v_mfma_f32_16x16x32_bf16 v[12:15], v[56:59], v[134:137], v[12:15]
	ds_write_b128 v110, v[182:185] offset:53248
	s_waitcnt lgkmcnt(4)
	v_mfma_f32_16x16x32_bf16 v[16:19], v[60:63], v[118:121], v[16:19]
	ds_write_b128 v110, v[186:189] offset:57344
	v_mfma_f32_16x16x32_bf16 v[20:23], v[60:63], v[126:129], v[20:23]
	ds_write_b128 v110, v[190:193] offset:61440
	v_mfma_f32_16x16x32_bf16 v[24:27], v[60:63], v[130:133], v[24:27]
	v_mfma_f32_16x16x32_bf16 v[28:31], v[60:63], v[134:137], v[28:31]
	s_waitcnt lgkmcnt(0)
	s_barrier
	ds_read_b128 v[32:35], v239 offset:32768
	ds_read_b128 v[40:43], v241 offset:32768
	ds_read_b128 v[44:47], v241 offset:34816
	ds_read_b128 v[48:51], v241 offset:36864
	ds_read_b128 v[52:55], v241 offset:38912
	ds_read_b128 v[36:39], v239 offset:34816
	s_waitcnt lgkmcnt(4)
	v_mfma_f32_16x16x32_bf16 v[0:3], v[32:35], v[40:43], v[0:3]
	ds_read_b128 v[56:59], v240 offset:32768
	s_waitcnt lgkmcnt(4)
	v_mfma_f32_16x16x32_bf16 v[4:7], v[32:35], v[44:47], v[4:7]
	ds_read_b128 v[118:121], v242 offset:32768
	s_waitcnt lgkmcnt(4)
	v_mfma_f32_16x16x32_bf16 v[8:11], v[32:35], v[48:51], v[8:11]
	ds_read_b128 v[126:129], v242 offset:34816
	s_waitcnt lgkmcnt(4)
	v_mfma_f32_16x16x32_bf16 v[12:15], v[32:35], v[52:55], v[12:15]
	ds_read_b128 v[130:133], v242 offset:36864
	s_waitcnt lgkmcnt(4)
	v_mfma_f32_16x16x32_bf16 v[16:19], v[36:39], v[40:43], v[16:19]
	ds_read_b128 v[134:137], v242 offset:38912
	v_mfma_f32_16x16x32_bf16 v[20:23], v[36:39], v[44:47], v[20:23]
	ds_read_b128 v[60:63], v240 offset:34816
	v_mfma_f32_16x16x32_bf16 v[24:27], v[36:39], v[48:51], v[24:27]
	v_mfma_f32_16x16x32_bf16 v[28:31], v[36:39], v[52:55], v[28:31]
	s_waitcnt lgkmcnt(4)
	v_mfma_f32_16x16x32_bf16 v[0:3], v[56:59], v[118:121], v[0:3]
	s_waitcnt lgkmcnt(3)
	v_mfma_f32_16x16x32_bf16 v[4:7], v[56:59], v[126:129], v[4:7]
	s_waitcnt lgkmcnt(2)
	v_mfma_f32_16x16x32_bf16 v[8:11], v[56:59], v[130:133], v[8:11]
	s_waitcnt lgkmcnt(1)
	v_mfma_f32_16x16x32_bf16 v[12:15], v[56:59], v[134:137], v[12:15]
	s_waitcnt lgkmcnt(0)
	v_mfma_f32_16x16x32_bf16 v[16:19], v[60:63], v[118:121], v[16:19]
	v_mfma_f32_16x16x32_bf16 v[20:23], v[60:63], v[126:129], v[20:23]
	v_mfma_f32_16x16x32_bf16 v[24:27], v[60:63], v[130:133], v[24:27]
	v_mfma_f32_16x16x32_bf16 v[28:31], v[60:63], v[134:137], v[28:31]
	s_waitcnt lgkmcnt(0)
	s_barrier
	s_nop 15
	ds_write_b32 v243, v0
	ds_write_b32 v243, v1 offset:528
	ds_write_b32 v243, v2 offset:1056
	ds_write_b32 v243, v3 offset:1584
	ds_write_b32 v243, v4 offset:64
	ds_write_b32 v243, v5 offset:592
	ds_write_b32 v243, v6 offset:1120
	ds_write_b32 v243, v7 offset:1648
	ds_write_b32 v243, v8 offset:128
	ds_write_b32 v243, v9 offset:656
	ds_write_b32 v243, v10 offset:1184
	ds_write_b32 v243, v11 offset:1712
	ds_write_b32 v243, v12 offset:192
	ds_write_b32 v243, v13 offset:720
	ds_write_b32 v243, v14 offset:1248
	ds_write_b32 v243, v15 offset:1776
	ds_write_b32 v243, v16 offset:8448
	ds_write_b32 v243, v17 offset:8976
	ds_write_b32 v243, v18 offset:9504
	ds_write_b32 v243, v19 offset:10032
	ds_write_b32 v243, v20 offset:8512
	ds_write_b32 v243, v21 offset:9040
	ds_write_b32 v243, v22 offset:9568
	ds_write_b32 v243, v23 offset:10096
	ds_write_b32 v243, v24 offset:8576
	ds_write_b32 v243, v25 offset:9104
	ds_write_b32 v243, v26 offset:9632
	ds_write_b32 v243, v27 offset:10160
	ds_write_b32 v243, v28 offset:8640
	ds_write_b32 v243, v29 offset:9168
	ds_write_b32 v243, v30 offset:9696
	ds_write_b32 v243, v31 offset:10224
	v_add_lshl_u32 v64, s14, v105, 11
	v_mov_b64_e32 v[48:49], v[64:65]
	v_mov_b32_e32 v49, v65
	v_lshl_add_u64 v[16:17], v[66:67], 0, v[48:49]
	v_lshl_add_u64 v[72:73], v[66:67], 0, v[48:49]
	s_and_b32 s24, s26, 0x7fffffc0
	v_or_b32_e32 v112, s24, v147
	v_mov_b32_e32 v113, v65
	s_lshl_b32 s14, s0, 2
	s_and_b32 s14, s14, 0xe00
	v_mov_b64_e32 v[94:95], s[34:35]
	v_lshl_or_b32 v64, v74, 2, s14
	v_readlane_b32 s52, v238, 32
	v_readlane_b32 s54, v238, 34
	v_readlane_b32 s55, v238, 35
	v_readlane_b32 s53, v238, 33
	v_readlane_b32 s56, v238, 36
	v_readlane_b32 s57, v238, 37
	v_readlane_b32 s58, v238, 38
	v_readlane_b32 s59, v238, 39
	v_readlane_b32 s60, v238, 40
	v_readlane_b32 s61, v238, 41
	v_readlane_b32 s62, v238, 42
	v_readlane_b32 s63, v238, 43
	v_readlane_b32 s64, v238, 44
	v_readlane_b32 s65, v238, 45
	v_readlane_b32 s66, v238, 46
	v_readlane_b32 s67, v238, 47
	v_or_b32_e32 v38, s24, v82
	v_mov_b32_e32 v39, v65
	v_lshlrev_b64 v[52:53], 12, v[38:39]
	v_add_u32_e32 v32, s24, v81
	v_mov_b32_e32 v33, v65
	v_lshlrev_b64 v[32:33], 12, v[32:33]
	v_lshl_add_u64 v[32:33], s[54:55], 0, v[32:33]
	v_lshl_add_u64 v[34:35], s[10:11], 0, v[52:53]
	v_lshrrev_b32_e32 v36, 3, v38
	v_add_u32_e32 v38, s24, v85
	v_mad_u64_u32 v[36:37], s[14:15], v36, s48, v[94:95]
	v_lshlrev_b64 v[38:39], 12, v[38:39]
	v_lshrrev_b32_e32 v44, 3, v112
	v_mov_b32_e32 v45, v65
	v_lshl_add_u64 v[38:39], s[16:17], 0, v[38:39]
	v_mad_u64_u32 v[40:41], s[14:15], v44, s48, v[94:95]
	v_or_b32_e32 v44, s24, v86
	v_lshlrev_b64 v[42:43], 12, v[44:45]
	v_lshrrev_b32_e32 v44, 3, v44
	v_mad_u64_u32 v[44:45], s[14:15], v44, s48, v[94:95]
	v_add_u32_e32 v50, s24, v88
	v_mov_b32_e32 v51, v65
	v_lshl_add_u64 v[42:43], s[10:11], 0, v[42:43]
	v_lshlrev_b64 v[48:49], 12, v[112:113]
	v_lshlrev_b64 v[46:47], 12, v[50:51]
	v_lshl_add_u64 v[46:47], s[16:17], 0, v[46:47]
	v_or_b32_e32 v52, s24, v89
	v_mov_b32_e32 v53, v65
	v_lshlrev_b64 v[50:51], 12, v[52:53]
	v_lshrrev_b32_e32 v52, 3, v52
	v_add_u32_e32 v54, s24, v91
	v_mov_b32_e32 v55, v65
	v_mad_u64_u32 v[52:53], s[14:15], v52, s48, v[94:95]
	v_lshlrev_b64 v[54:55], 12, v[54:55]
	v_lshl_add_u64 v[48:49], s[70:71], 0, v[48:49]
	v_lshl_add_u64 v[50:51], s[10:11], 0, v[50:51]
	v_lshl_add_u64 v[54:55], s[16:17], 0, v[54:55]
	s_mov_b32 s14, 0
	s_waitcnt lgkmcnt(0)
	s_barrier

.LBB0_882:
	s_cmpk_gt_i32 s2, 0x3ff
	s_mov_b64 s[10:11], -1
	s_cbranch_scc0 .LBB0_922
	s_lshl_b32 s10, s2, 3
	s_add_i32 s10, s10, 0x7fffe000
	s_and_b32 s14, s10, 0x7fffffc0
	s_addk_i32 s14, 0x4000
	v_or_b32_e32 v0, s14, v105
	v_lshlrev_b32_e32 v48, 11, v0
	v_mov_b32_e32 v49, v65
	v_lshl_add_u64 v[0:1], v[68:69], 0, v[48:49]
	s_lshl_b32 s10, s2, 7
	s_and_b32 s20, s10, 0x380
	v_add_lshl_u32 v64, s20, v105, 11
	v_lshl_add_u64 v[78:79], v[76:77], 0, v[64:65]
	v_readfirstlane_b32 s98, v68
	v_readfirstlane_b32 s99, v69
	v_readfirstlane_b32 s100, v76
	v_readfirstlane_b32 s101, v77
	s_mul_i32 s11, s14, 0x800
	s_add_u32 s98, s98, s11
	s_addc_u32 s99, s99, 0
	s_mul_i32 s11, s20, 0x800
	s_add_u32 s100, s100, s11
	s_addc_u32 s101, s101, 0
	v_lshrrev_b32_e32 v246, 3, v100
	v_and_b32_e32 v247, 7, v100
	v_bfe_u32 v244, v100, 4, 3
	v_xor_b32_e32 v244, v244, v247
	v_lshlrev_b32_e32 v244, 4, v244
	v_lshl_or_b32 v153, v246, 7, v244
	v_lshlrev_b32_e32 v245, 4, v247
	v_mul_u32_u24_e32 v115, 0x800, v246
	v_add_u32_e32 v115, v115, v245
	v_add_u32_e32 v116, 0x10000, v115
	v_mul_u32_u24_e32 v122, 0x800, v246
	v_add_u32_e32 v122, v122, v245
	v_add_u32_e32 v123, 0x10000, v122
	v_add_u32_e32 v124, 0x20000, v122
	v_add_u32_e32 v146, 0x30000, v122
	v_and_b32_e32 v244, 15, v100
	v_bfe_u32 v245, v100, 4, 2
	v_bfe_u32 v246, v100, 1, 3
	v_xor_b32_e32 v247, v245, v246
	v_lshlrev_b32_e32 v247, 4, v247
	v_lshl_or_b32 v247, v244, 7, v247
	v_bfe_u32 v246, v100, 7, 1
	v_lshl_add_u32 v239, v246, 12, v247
	v_xor_b32_e32 v240, 64, v239
	v_bfe_u32 v246, v100, 6, 1
	v_lshl_add_u32 v241, v246, 13, v247
	v_add_u32_e32 v241, 0x4000, v241
	v_xor_b32_e32 v242, 64, v241
	v_bfe_u32 v247, v100, 7, 1
	v_lshlrev_b32_e32 v247, 5, v247
	v_lshl_add_u32 v247, v245, 2, v247
	v_mul_u32_u24_e32 v247, 0x84, v247
	v_lshl_add_u32 v247, v246, 6, v247
	v_add_u32_e32 v247, v247, v244
	v_lshlrev_b32_e32 v243, 2, v247
	global_load_dwordx4 v[138:141], v115, s[98:99]
	global_load_dwordx4 v[142:145], v116, s[98:99]
	global_load_dwordx4 v[148:151], v122, s[100:101]
	global_load_dwordx4 v[154:157], v123, s[100:101]
	global_load_dwordx4 v[158:161], v124, s[100:101]
	global_load_dwordx4 v[162:165], v146, s[100:101]
	global_load_dwordx4 v[166:169], v115, s[98:99] offset:128
	global_load_dwordx4 v[170:173], v116, s[98:99] offset:128
	global_load_dwordx4 v[174:177], v122, s[100:101] offset:128
	global_load_dwordx4 v[178:181], v123, s[100:101] offset:128
	global_load_dwordx4 v[182:185], v124, s[100:101] offset:128
	global_load_dwordx4 v[186:189], v146, s[100:101] offset:128
	s_barrier
	s_waitcnt vmcnt(6)
	ds_write_b128 v153, v[138:141]
	ds_write_b128 v153, v[142:145] offset:4096
	ds_write_b128 v153, v[148:151] offset:16384
	ds_write_b128 v153, v[154:157] offset:20480
	ds_write_b128 v153, v[158:161] offset:24576
	ds_write_b128 v153, v[162:165] offset:28672
	global_load_dwordx4 v[138:141], v115, s[98:99] offset:256
	global_load_dwordx4 v[142:145], v116, s[98:99] offset:256
	global_load_dwordx4 v[148:151], v122, s[100:101] offset:256
	global_load_dwordx4 v[154:157], v123, s[100:101] offset:256
	global_load_dwordx4 v[158:161], v124, s[100:101] offset:256
	global_load_dwordx4 v[162:165], v146, s[100:101] offset:256
	s_waitcnt lgkmcnt(0)
	s_barrier
	ds_read_b128 v[32:35], v239
	ds_read_b128 v[40:43], v241
	ds_read_b128 v[44:47], v241 offset:2048
	ds_read_b128 v[48:51], v241 offset:4096
	ds_read_b128 v[52:55], v241 offset:6144
	ds_read_b128 v[36:39], v239 offset:2048
	s_waitcnt lgkmcnt(4)
	v_mfma_f32_16x16x32_bf16 v[0:3], v[32:35], v[40:43], 0
	ds_read_b128 v[56:59], v240
	s_waitcnt lgkmcnt(4)
	v_mfma_f32_16x16x32_bf16 v[4:7], v[32:35], v[44:47], 0
	ds_read_b128 v[118:121], v242
	s_waitcnt lgkmcnt(4)
	v_mfma_f32_16x16x32_bf16 v[8:11], v[32:35], v[48:51], 0
	ds_read_b128 v[126:129], v242 offset:2048
	s_waitcnt lgkmcnt(4)
	v_mfma_f32_16x16x32_bf16 v[12:15], v[32:35], v[52:55], 0
	ds_read_b128 v[130:133], v242 offset:4096
	s_waitcnt lgkmcnt(4)
	v_mfma_f32_16x16x32_bf16 v[16:19], v[36:39], v[40:43], 0
	ds_read_b128 v[134:137], v242 offset:6144
	v_mfma_f32_16x16x32_bf16 v[20:23], v[36:39], v[44:47], 0
	ds_read_b128 v[60:63], v240 offset:2048
	v_mfma_f32_16x16x32_bf16 v[24:27], v[36:39], v[48:51], 0
	v_mfma_f32_16x16x32_bf16 v[28:31], v[36:39], v[52:55], 0
	s_waitcnt lgkmcnt(4)
	v_mfma_f32_16x16x32_bf16 v[0:3], v[56:59], v[118:121], v[0:3]
	s_waitcnt vmcnt(6)
	ds_write_b128 v153, v[166:169] offset:32768
	s_waitcnt lgkmcnt(4)
	v_mfma_f32_16x16x32_bf16 v[4:7], v[56:59], v[126:129], v[4:7]
	ds_write_b128 v153, v[170:173] offset:36864
	s_waitcnt lgkmcnt(4)
	v_mfma_f32_16x16x32_bf16 v[8:11], v[56:59], v[130:133], v[8:11]
	ds_write_b128 v153, v[174:177] offset:49152
	global_load_dwordx4 v[166:169], v115, s[98:99] offset:384
	s_waitcnt lgkmcnt(4)
	v_mfma_f32_16x16x32_bf16 v[12:15], v[56:59], v[134:137], v[12:15]
	ds_write_b128 v153, v[178:181] offset:53248
	global_load_dwordx4 v[170:173], v116, s[98:99] offset:384
	s_waitcnt lgkmcnt(4)
	v_mfma_f32_16x16x32_bf16 v[16:19], v[60:63], v[118:121], v[16:19]
	ds_write_b128 v153, v[182:185] offset:57344
	global_load_dwordx4 v[174:177], v122, s[100:101] offset:384
	v_mfma_f32_16x16x32_bf16 v[20:23], v[60:63], v[126:129], v[20:23]
	ds_write_b128 v153, v[186:189] offset:61440
	global_load_dwordx4 v[178:181], v123, s[100:101] offset:384
	v_mfma_f32_16x16x32_bf16 v[24:27], v[60:63], v[130:133], v[24:27]
	global_load_dwordx4 v[182:185], v124, s[100:101] offset:384
	v_mfma_f32_16x16x32_bf16 v[28:31], v[60:63], v[134:137], v[28:31]
	global_load_dwordx4 v[186:189], v146, s[100:101] offset:384
	s_waitcnt lgkmcnt(0)
	s_barrier
	ds_read_b128 v[32:35], v239 offset:32768
	ds_read_b128 v[40:43], v241 offset:32768
	ds_read_b128 v[44:47], v241 offset:34816
	ds_read_b128 v[48:51], v241 offset:36864
	ds_read_b128 v[52:55], v241 offset:38912
	ds_read_b128 v[36:39], v239 offset:34816
	s_waitcnt lgkmcnt(4)
	v_mfma_f32_16x16x32_bf16 v[0:3], v[32:35], v[40:43], v[0:3]
	ds_read_b128 v[56:59], v240 offset:32768
	s_waitcnt lgkmcnt(4)
	v_mfma_f32_16x16x32_bf16 v[4:7], v[32:35], v[44:47], v[4:7]
	ds_read_b128 v[118:121], v242 offset:32768
	s_waitcnt lgkmcnt(4)
	v_mfma_f32_16x16x32_bf16 v[8:11], v[32:35], v[48:51], v[8:11]
	ds_read_b128 v[126:129], v242 offset:34816
	s_waitcnt lgkmcnt(4)
	v_mfma_f32_16x16x32_bf16 v[12:15], v[32:35], v[52:55], v[12:15]
	ds_read_b128 v[130:133], v242 offset:36864
	s_waitcnt lgkmcnt(4)
	v_mfma_f32_16x16x32_bf16 v[16:19], v[36:39], v[40:43], v[16:19]
	ds_read_b128 v[134:137], v242 offset:38912
	v_mfma_f32_16x16x32_bf16 v[20:23], v[36:39], v[44:47], v[20:23]
	ds_read_b128 v[60:63], v240 offset:34816
	v_mfma_f32_16x16x32_bf16 v[24:27], v[36:39], v[48:51], v[24:27]
	v_mfma_f32_16x16x32_bf16 v[28:31], v[36:39], v[52:55], v[28:31]
	s_waitcnt lgkmcnt(4)
	v_mfma_f32_16x16x32_bf16 v[0:3], v[56:59], v[118:121], v[0:3]
	s_waitcnt vmcnt(6)
	ds_write_b128 v153, v[138:141]
	s_waitcnt lgkmcnt(4)
	v_mfma_f32_16x16x32_bf16 v[4:7], v[56:59], v[126:129], v[4:7]
	ds_write_b128 v153, v[142:145] offset:4096
	s_waitcnt lgkmcnt(4)
	v_mfma_f32_16x16x32_bf16 v[8:11], v[56:59], v[130:133], v[8:11]
	ds_write_b128 v153, v[148:151] offset:16384
	global_load_dwordx4 v[138:141], v115, s[98:99] offset:512
	s_waitcnt lgkmcnt(4)
	v_mfma_f32_16x16x32_bf16 v[12:15], v[56:59], v[134:137], v[12:15]
	ds_write_b128 v153, v[154:157] offset:20480
	global_load_dwordx4 v[142:145], v116, s[98:99] offset:512
	s_waitcnt lgkmcnt(4)
	v_mfma_f32_16x16x32_bf16 v[16:19], v[60:63], v[118:121], v[16:19]
	ds_write_b128 v153, v[158:161] offset:24576
	global_load_dwordx4 v[148:151], v122, s[100:101] offset:512
	v_mfma_f32_16x16x32_bf16 v[20:23], v[60:63], v[126:129], v[20:23]
	ds_write_b128 v153, v[162:165] offset:28672
	global_load_dwordx4 v[154:157], v123, s[100:101] offset:512
	v_mfma_f32_16x16x32_bf16 v[24:27], v[60:63], v[130:133], v[24:27]
	global_load_dwordx4 v[158:161], v124, s[100:101] offset:512
	v_mfma_f32_16x16x32_bf16 v[28:31], v[60:63], v[134:137], v[28:31]
	global_load_dwordx4 v[162:165], v146, s[100:101] offset:512
	s_waitcnt lgkmcnt(0)
	s_barrier
	ds_read_b128 v[32:35], v239
	ds_read_b128 v[40:43], v241
	ds_read_b128 v[44:47], v241 offset:2048
	ds_read_b128 v[48:51], v241 offset:4096
	ds_read_b128 v[52:55], v241 offset:6144
	ds_read_b128 v[36:39], v239 offset:2048
	s_waitcnt lgkmcnt(4)
	v_mfma_f32_16x16x32_bf16 v[0:3], v[32:35], v[40:43], v[0:3]
	ds_read_b128 v[56:59], v240
	s_waitcnt lgkmcnt(4)
	v_mfma_f32_16x16x32_bf16 v[4:7], v[32:35], v[44:47], v[4:7]
	ds_read_b128 v[118:121], v242
	s_waitcnt lgkmcnt(4)
	v_mfma_f32_16x16x32_bf16 v[8:11], v[32:35], v[48:51], v[8:11]
	ds_read_b128 v[126:129], v242 offset:2048
	s_waitcnt lgkmcnt(4)
	v_mfma_f32_16x16x32_bf16 v[12:15], v[32:35], v[52:55], v[12:15]
	ds_read_b128 v[130:133], v242 offset:4096
	s_waitcnt lgkmcnt(4)
	v_mfma_f32_16x16x32_bf16 v[16:19], v[36:39], v[40:43], v[16:19]
	ds_read_b128 v[134:137], v242 offset:6144
	v_mfma_f32_16x16x32_bf16 v[20:23], v[36:39], v[44:47], v[20:23]
	ds_read_b128 v[60:63], v240 offset:2048
	v_mfma_f32_16x16x32_bf16 v[24:27], v[36:39], v[48:51], v[24:27]
	v_mfma_f32_16x16x32_bf16 v[28:31], v[36:39], v[52:55], v[28:31]
	s_waitcnt lgkmcnt(4)
	v_mfma_f32_16x16x32_bf16 v[0:3], v[56:59], v[118:121], v[0:3]
	s_waitcnt vmcnt(6)
	ds_write_b128 v153, v[166:169] offset:32768
	s_waitcnt lgkmcnt(4)
	v_mfma_f32_16x16x32_bf16 v[4:7], v[56:59], v[126:129], v[4:7]
	ds_write_b128 v153, v[170:173] offset:36864
	s_waitcnt lgkmcnt(4)
	v_mfma_f32_16x16x32_bf16 v[8:11], v[56:59], v[130:133], v[8:11]
	ds_write_b128 v153, v[174:177] offset:49152
	global_load_dwordx4 v[166:169], v115, s[98:99] offset:640
	s_waitcnt lgkmcnt(4)
	v_mfma_f32_16x16x32_bf16 v[12:15], v[56:59], v[134:137], v[12:15]
	ds_write_b128 v153, v[178:181] offset:53248
	global_load_dwordx4 v[170:173], v116, s[98:99] offset:640
	s_waitcnt lgkmcnt(4)
	v_mfma_f32_16x16x32_bf16 v[16:19], v[60:63], v[118:121], v[16:19]
	ds_write_b128 v153, v[182:185] offset:57344
	global_load_dwordx4 v[174:177], v122, s[100:101] offset:640
	v_mfma_f32_16x16x32_bf16 v[20:23], v[60:63], v[126:129], v[20:23]
	ds_write_b128 v153, v[186:189] offset:61440
	global_load_dwordx4 v[178:181], v123, s[100:101] offset:640
	v_mfma_f32_16x16x32_bf16 v[24:27], v[60:63], v[130:133], v[24:27]
	global_load_dwordx4 v[182:185], v124, s[100:101] offset:640
	v_mfma_f32_16x16x32_bf16 v[28:31], v[60:63], v[134:137], v[28:31]
	global_load_dwordx4 v[186:189], v146, s[100:101] offset:640
	s_waitcnt lgkmcnt(0)
	s_barrier
	ds_read_b128 v[32:35], v239 offset:32768
	ds_read_b128 v[40:43], v241 offset:32768
	ds_read_b128 v[44:47], v241 offset:34816
	ds_read_b128 v[48:51], v241 offset:36864
	ds_read_b128 v[52:55], v241 offset:38912
	ds_read_b128 v[36:39], v239 offset:34816
	s_waitcnt lgkmcnt(4)
	v_mfma_f32_16x16x32_bf16 v[0:3], v[32:35], v[40:43], v[0:3]
	ds_read_b128 v[56:59], v240 offset:32768
	s_waitcnt lgkmcnt(4)
	v_mfma_f32_16x16x32_bf16 v[4:7], v[32:35], v[44:47], v[4:7]
	ds_read_b128 v[118:121], v242 offset:32768
	s_waitcnt lgkmcnt(4)
	v_mfma_f32_16x16x32_bf16 v[8:11], v[32:35], v[48:51], v[8:11]
	ds_read_b128 v[126:129], v242 offset:34816
	s_waitcnt lgkmcnt(4)
	v_mfma_f32_16x16x32_bf16 v[12:15], v[32:35], v[52:55], v[12:15]
	ds_read_b128 v[130:133], v242 offset:36864
	s_waitcnt lgkmcnt(4)
	v_mfma_f32_16x16x32_bf16 v[16:19], v[36:39], v[40:43], v[16:19]
	ds_read_b128 v[134:137], v242 offset:38912
	v_mfma_f32_16x16x32_bf16 v[20:23], v[36:39], v[44:47], v[20:23]
	ds_read_b128 v[60:63], v240 offset:34816
	v_mfma_f32_16x16x32_bf16 v[24:27], v[36:39], v[48:51], v[24:27]
	v_mfma_f32_16x16x32_bf16 v[28:31], v[36:39], v[52:55], v[28:31]
	s_waitcnt lgkmcnt(4)
	v_mfma_f32_16x16x32_bf16 v[0:3], v[56:59], v[118:121], v[0:3]
	s_waitcnt vmcnt(6)
	ds_write_b128 v153, v[138:141]
	s_waitcnt lgkmcnt(4)
	v_mfma_f32_16x16x32_bf16 v[4:7], v[56:59], v[126:129], v[4:7]
	ds_write_b128 v153, v[142:145] offset:4096
	s_waitcnt lgkmcnt(4)
	v_mfma_f32_16x16x32_bf16 v[8:11], v[56:59], v[130:133], v[8:11]
	ds_write_b128 v153, v[148:151] offset:16384
	global_load_dwordx4 v[138:141], v115, s[98:99] offset:768
	s_waitcnt lgkmcnt(4)
	v_mfma_f32_16x16x32_bf16 v[12:15], v[56:59], v[134:137], v[12:15]
	ds_write_b128 v153, v[154:157] offset:20480
	global_load_dwordx4 v[142:145], v116, s[98:99] offset:768
	s_waitcnt lgkmcnt(4)
	v_mfma_f32_16x16x32_bf16 v[16:19], v[60:63], v[118:121], v[16:19]
	ds_write_b128 v153, v[158:161] offset:24576
	global_load_dwordx4 v[148:151], v122, s[100:101] offset:768
	v_mfma_f32_16x16x32_bf16 v[20:23], v[60:63], v[126:129], v[20:23]
	ds_write_b128 v153, v[162:165] offset:28672
	global_load_dwordx4 v[154:157], v123, s[100:101] offset:768
	v_mfma_f32_16x16x32_bf16 v[24:27], v[60:63], v[130:133], v[24:27]
	global_load_dwordx4 v[158:161], v124, s[100:101] offset:768
	v_mfma_f32_16x16x32_bf16 v[28:31], v[60:63], v[134:137], v[28:31]
	global_load_dwordx4 v[162:165], v146, s[100:101] offset:768
	s_waitcnt lgkmcnt(0)
	s_barrier
	ds_read_b128 v[32:35], v239
	ds_read_b128 v[40:43], v241
	ds_read_b128 v[44:47], v241 offset:2048
	ds_read_b128 v[48:51], v241 offset:4096
	ds_read_b128 v[52:55], v241 offset:6144
	ds_read_b128 v[36:39], v239 offset:2048
	s_waitcnt lgkmcnt(4)
	v_mfma_f32_16x16x32_bf16 v[0:3], v[32:35], v[40:43], v[0:3]
	ds_read_b128 v[56:59], v240
	s_waitcnt lgkmcnt(4)
	v_mfma_f32_16x16x32_bf16 v[4:7], v[32:35], v[44:47], v[4:7]
	ds_read_b128 v[118:121], v242
	s_waitcnt lgkmcnt(4)
	v_mfma_f32_16x16x32_bf16 v[8:11], v[32:35], v[48:51], v[8:11]
	ds_read_b128 v[126:129], v242 offset:2048
	s_waitcnt lgkmcnt(4)
	v_mfma_f32_16x16x32_bf16 v[12:15], v[32:35], v[52:55], v[12:15]
	ds_read_b128 v[130:133], v242 offset:4096
	s_waitcnt lgkmcnt(4)
	v_mfma_f32_16x16x32_bf16 v[16:19], v[36:39], v[40:43], v[16:19]
	ds_read_b128 v[134:137], v242 offset:6144
	v_mfma_f32_16x16x32_bf16 v[20:23], v[36:39], v[44:47], v[20:23]
	ds_read_b128 v[60:63], v240 offset:2048
	v_mfma_f32_16x16x32_bf16 v[24:27], v[36:39], v[48:51], v[24:27]
	v_mfma_f32_16x16x32_bf16 v[28:31], v[36:39], v[52:55], v[28:31]
	s_waitcnt lgkmcnt(4)
	v_mfma_f32_16x16x32_bf16 v[0:3], v[56:59], v[118:121], v[0:3]
	s_waitcnt vmcnt(6)
	ds_write_b128 v153, v[166:169] offset:32768
	s_waitcnt lgkmcnt(4)
	v_mfma_f32_16x16x32_bf16 v[4:7], v[56:59], v[126:129], v[4:7]
	ds_write_b128 v153, v[170:173] offset:36864
	s_waitcnt lgkmcnt(4)
	v_mfma_f32_16x16x32_bf16 v[8:11], v[56:59], v[130:133], v[8:11]
	ds_write_b128 v153, v[174:177] offset:49152
	global_load_dwordx4 v[166:169], v115, s[98:99] offset:896
	s_waitcnt lgkmcnt(4)
	v_mfma_f32_16x16x32_bf16 v[12:15], v[56:59], v[134:137], v[12:15]
	ds_write_b128 v153, v[178:181] offset:53248
	global_load_dwordx4 v[170:173], v116, s[98:99] offset:896
	s_waitcnt lgkmcnt(4)
	v_mfma_f32_16x16x32_bf16 v[16:19], v[60:63], v[118:121], v[16:19]
	ds_write_b128 v153, v[182:185] offset:57344
	global_load_dwordx4 v[174:177], v122, s[100:101] offset:896
	v_mfma_f32_16x16x32_bf16 v[20:23], v[60:63], v[126:129], v[20:23]
	ds_write_b128 v153, v[186:189] offset:61440
	global_load_dwordx4 v[178:181], v123, s[100:101] offset:896
	v_mfma_f32_16x16x32_bf16 v[24:27], v[60:63], v[130:133], v[24:27]
	global_load_dwordx4 v[182:185], v124, s[100:101] offset:896
	v_mfma_f32_16x16x32_bf16 v[28:31], v[60:63], v[134:137], v[28:31]
	global_load_dwordx4 v[186:189], v146, s[100:101] offset:896
	s_waitcnt lgkmcnt(0)
	s_barrier
	ds_read_b128 v[32:35], v239 offset:32768
	ds_read_b128 v[40:43], v241 offset:32768
	ds_read_b128 v[44:47], v241 offset:34816
	ds_read_b128 v[48:51], v241 offset:36864
	ds_read_b128 v[52:55], v241 offset:38912
	ds_read_b128 v[36:39], v239 offset:34816
	s_waitcnt lgkmcnt(4)
	v_mfma_f32_16x16x32_bf16 v[0:3], v[32:35], v[40:43], v[0:3]
	ds_read_b128 v[56:59], v240 offset:32768
	s_waitcnt lgkmcnt(4)
	v_mfma_f32_16x16x32_bf16 v[4:7], v[32:35], v[44:47], v[4:7]
	ds_read_b128 v[118:121], v242 offset:32768
	s_waitcnt lgkmcnt(4)
	v_mfma_f32_16x16x32_bf16 v[8:11], v[32:35], v[48:51], v[8:11]
	ds_read_b128 v[126:129], v242 offset:34816
	s_waitcnt lgkmcnt(4)
	v_mfma_f32_16x16x32_bf16 v[12:15], v[32:35], v[52:55], v[12:15]
	ds_read_b128 v[130:133], v242 offset:36864
	s_waitcnt lgkmcnt(4)
	v_mfma_f32_16x16x32_bf16 v[16:19], v[36:39], v[40:43], v[16:19]
	ds_read_b128 v[134:137], v242 offset:38912
	v_mfma_f32_16x16x32_bf16 v[20:23], v[36:39], v[44:47], v[20:23]
	ds_read_b128 v[60:63], v240 offset:34816
	v_mfma_f32_16x16x32_bf16 v[24:27], v[36:39], v[48:51], v[24:27]
	v_mfma_f32_16x16x32_bf16 v[28:31], v[36:39], v[52:55], v[28:31]
	s_waitcnt lgkmcnt(4)
	v_mfma_f32_16x16x32_bf16 v[0:3], v[56:59], v[118:121], v[0:3]
	s_waitcnt vmcnt(6)
	ds_write_b128 v153, v[138:141]
	s_waitcnt lgkmcnt(4)
	v_mfma_f32_16x16x32_bf16 v[4:7], v[56:59], v[126:129], v[4:7]
	ds_write_b128 v153, v[142:145] offset:4096
	s_waitcnt lgkmcnt(4)
	v_mfma_f32_16x16x32_bf16 v[8:11], v[56:59], v[130:133], v[8:11]
	ds_write_b128 v153, v[148:151] offset:16384
	global_load_dwordx4 v[138:141], v115, s[98:99] offset:1024
	s_waitcnt lgkmcnt(4)
	v_mfma_f32_16x16x32_bf16 v[12:15], v[56:59], v[134:137], v[12:15]
	ds_write_b128 v153, v[154:157] offset:20480
	global_load_dwordx4 v[142:145], v116, s[98:99] offset:1024
	s_waitcnt lgkmcnt(4)
	v_mfma_f32_16x16x32_bf16 v[16:19], v[60:63], v[118:121], v[16:19]
	ds_write_b128 v153, v[158:161] offset:24576
	global_load_dwordx4 v[148:151], v122, s[100:101] offset:1024
	v_mfma_f32_16x16x32_bf16 v[20:23], v[60:63], v[126:129], v[20:23]
	ds_write_b128 v153, v[162:165] offset:28672
	global_load_dwordx4 v[154:157], v123, s[100:101] offset:1024
	v_mfma_f32_16x16x32_bf16 v[24:27], v[60:63], v[130:133], v[24:27]
	global_load_dwordx4 v[158:161], v124, s[100:101] offset:1024
	v_mfma_f32_16x16x32_bf16 v[28:31], v[60:63], v[134:137], v[28:31]
	global_load_dwordx4 v[162:165], v146, s[100:101] offset:1024
	s_waitcnt lgkmcnt(0)
	s_barrier
	ds_read_b128 v[32:35], v239
	ds_read_b128 v[40:43], v241
	ds_read_b128 v[44:47], v241 offset:2048
	ds_read_b128 v[48:51], v241 offset:4096
	ds_read_b128 v[52:55], v241 offset:6144
	ds_read_b128 v[36:39], v239 offset:2048
	s_waitcnt lgkmcnt(4)
	v_mfma_f32_16x16x32_bf16 v[0:3], v[32:35], v[40:43], v[0:3]
	ds_read_b128 v[56:59], v240
	s_waitcnt lgkmcnt(4)
	v_mfma_f32_16x16x32_bf16 v[4:7], v[32:35], v[44:47], v[4:7]
	ds_read_b128 v[118:121], v242
	s_waitcnt lgkmcnt(4)
	v_mfma_f32_16x16x32_bf16 v[8:11], v[32:35], v[48:51], v[8:11]
	ds_read_b128 v[126:129], v242 offset:2048
	s_waitcnt lgkmcnt(4)
	v_mfma_f32_16x16x32_bf16 v[12:15], v[32:35], v[52:55], v[12:15]
	ds_read_b128 v[130:133], v242 offset:4096
	s_waitcnt lgkmcnt(4)
	v_mfma_f32_16x16x32_bf16 v[16:19], v[36:39], v[40:43], v[16:19]
	ds_read_b128 v[134:137], v242 offset:6144
	v_mfma_f32_16x16x32_bf16 v[20:23], v[36:39], v[44:47], v[20:23]
	ds_read_b128 v[60:63], v240 offset:2048
	v_mfma_f32_16x16x32_bf16 v[24:27], v[36:39], v[48:51], v[24:27]
	v_mfma_f32_16x16x32_bf16 v[28:31], v[36:39], v[52:55], v[28:31]
	s_waitcnt lgkmcnt(4)
	v_mfma_f32_16x16x32_bf16 v[0:3], v[56:59], v[118:121], v[0:3]
	s_waitcnt vmcnt(6)
	ds_write_b128 v153, v[166:169] offset:32768
	s_waitcnt lgkmcnt(4)
	v_mfma_f32_16x16x32_bf16 v[4:7], v[56:59], v[126:129], v[4:7]
	ds_write_b128 v153, v[170:173] offset:36864
	s_waitcnt lgkmcnt(4)
	v_mfma_f32_16x16x32_bf16 v[8:11], v[56:59], v[130:133], v[8:11]
	ds_write_b128 v153, v[174:177] offset:49152
	global_load_dwordx4 v[166:169], v115, s[98:99] offset:1152
	s_waitcnt lgkmcnt(4)
	v_mfma_f32_16x16x32_bf16 v[12:15], v[56:59], v[134:137], v[12:15]
	ds_write_b128 v153, v[178:181] offset:53248
	global_load_dwordx4 v[170:173], v116, s[98:99] offset:1152
	s_waitcnt lgkmcnt(4)
	v_mfma_f32_16x16x32_bf16 v[16:19], v[60:63], v[118:121], v[16:19]
	ds_write_b128 v153, v[182:185] offset:57344
	global_load_dwordx4 v[174:177], v122, s[100:101] offset:1152
	v_mfma_f32_16x16x32_bf16 v[20:23], v[60:63], v[126:129], v[20:23]
	ds_write_b128 v153, v[186:189] offset:61440
	global_load_dwordx4 v[178:181], v123, s[100:101] offset:1152
	v_mfma_f32_16x16x32_bf16 v[24:27], v[60:63], v[130:133], v[24:27]
	global_load_dwordx4 v[182:185], v124, s[100:101] offset:1152
	v_mfma_f32_16x16x32_bf16 v[28:31], v[60:63], v[134:137], v[28:31]
	global_load_dwordx4 v[186:189], v146, s[100:101] offset:1152
	s_waitcnt lgkmcnt(0)
	s_barrier
	ds_read_b128 v[32:35], v239 offset:32768
	ds_read_b128 v[40:43], v241 offset:32768
	ds_read_b128 v[44:47], v241 offset:34816
	ds_read_b128 v[48:51], v241 offset:36864
	ds_read_b128 v[52:55], v241 offset:38912
	ds_read_b128 v[36:39], v239 offset:34816
	s_waitcnt lgkmcnt(4)
	v_mfma_f32_16x16x32_bf16 v[0:3], v[32:35], v[40:43], v[0:3]
	ds_read_b128 v[56:59], v240 offset:32768
	s_waitcnt lgkmcnt(4)
	v_mfma_f32_16x16x32_bf16 v[4:7], v[32:35], v[44:47], v[4:7]
	ds_read_b128 v[118:121], v242 offset:32768
	s_waitcnt lgkmcnt(4)
	v_mfma_f32_16x16x32_bf16 v[8:11], v[32:35], v[48:51], v[8:11]
	ds_read_b128 v[126:129], v242 offset:34816
	s_waitcnt lgkmcnt(4)
	v_mfma_f32_16x16x32_bf16 v[12:15], v[32:35], v[52:55], v[12:15]
	ds_read_b128 v[130:133], v242 offset:36864
	s_waitcnt lgkmcnt(4)
	v_mfma_f32_16x16x32_bf16 v[16:19], v[36:39], v[40:43], v[16:19]
	ds_read_b128 v[134:137], v242 offset:38912
	v_mfma_f32_16x16x32_bf16 v[20:23], v[36:39], v[44:47], v[20:23]
	ds_read_b128 v[60:63], v240 offset:34816
	v_mfma_f32_16x16x32_bf16 v[24:27], v[36:39], v[48:51], v[24:27]
	v_mfma_f32_16x16x32_bf16 v[28:31], v[36:39], v[52:55], v[28:31]
	s_waitcnt lgkmcnt(4)
	v_mfma_f32_16x16x32_bf16 v[0:3], v[56:59], v[118:121], v[0:3]
	s_waitcnt vmcnt(6)
	ds_write_b128 v153, v[138:141]
	s_waitcnt lgkmcnt(4)
	v_mfma_f32_16x16x32_bf16 v[4:7], v[56:59], v[126:129], v[4:7]
	ds_write_b128 v153, v[142:145] offset:4096
	s_waitcnt lgkmcnt(4)
	v_mfma_f32_16x16x32_bf16 v[8:11], v[56:59], v[130:133], v[8:11]
	ds_write_b128 v153, v[148:151] offset:16384
	global_load_dwordx4 v[138:141], v115, s[98:99] offset:1280
	s_waitcnt lgkmcnt(4)
	v_mfma_f32_16x16x32_bf16 v[12:15], v[56:59], v[134:137], v[12:15]
	ds_write_b128 v153, v[154:157] offset:20480
	global_load_dwordx4 v[142:145], v116, s[98:99] offset:1280
	s_waitcnt lgkmcnt(4)
	v_mfma_f32_16x16x32_bf16 v[16:19], v[60:63], v[118:121], v[16:19]
	ds_write_b128 v153, v[158:161] offset:24576
	global_load_dwordx4 v[148:151], v122, s[100:101] offset:1280
	v_mfma_f32_16x16x32_bf16 v[20:23], v[60:63], v[126:129], v[20:23]
	ds_write_b128 v153, v[162:165] offset:28672
	global_load_dwordx4 v[154:157], v123, s[100:101] offset:1280
	v_mfma_f32_16x16x32_bf16 v[24:27], v[60:63], v[130:133], v[24:27]
	global_load_dwordx4 v[158:161], v124, s[100:101] offset:1280
	v_mfma_f32_16x16x32_bf16 v[28:31], v[60:63], v[134:137], v[28:31]
	global_load_dwordx4 v[162:165], v146, s[100:101] offset:1280
	s_waitcnt lgkmcnt(0)
	s_barrier
	ds_read_b128 v[32:35], v239
	ds_read_b128 v[40:43], v241
	ds_read_b128 v[44:47], v241 offset:2048
	ds_read_b128 v[48:51], v241 offset:4096
	ds_read_b128 v[52:55], v241 offset:6144
	ds_read_b128 v[36:39], v239 offset:2048
	s_waitcnt lgkmcnt(4)
	v_mfma_f32_16x16x32_bf16 v[0:3], v[32:35], v[40:43], v[0:3]
	ds_read_b128 v[56:59], v240
	s_waitcnt lgkmcnt(4)
	v_mfma_f32_16x16x32_bf16 v[4:7], v[32:35], v[44:47], v[4:7]
	ds_read_b128 v[118:121], v242
	s_waitcnt lgkmcnt(4)
	v_mfma_f32_16x16x32_bf16 v[8:11], v[32:35], v[48:51], v[8:11]
	ds_read_b128 v[126:129], v242 offset:2048
	s_waitcnt lgkmcnt(4)
	v_mfma_f32_16x16x32_bf16 v[12:15], v[32:35], v[52:55], v[12:15]
	ds_read_b128 v[130:133], v242 offset:4096
	s_waitcnt lgkmcnt(4)
	v_mfma_f32_16x16x32_bf16 v[16:19], v[36:39], v[40:43], v[16:19]
	ds_read_b128 v[134:137], v242 offset:6144
	v_mfma_f32_16x16x32_bf16 v[20:23], v[36:39], v[44:47], v[20:23]
	ds_read_b128 v[60:63], v240 offset:2048
	v_mfma_f32_16x16x32_bf16 v[24:27], v[36:39], v[48:51], v[24:27]
	v_mfma_f32_16x16x32_bf16 v[28:31], v[36:39], v[52:55], v[28:31]
	s_waitcnt lgkmcnt(4)
	v_mfma_f32_16x16x32_bf16 v[0:3], v[56:59], v[118:121], v[0:3]
	s_waitcnt vmcnt(6)
	ds_write_b128 v153, v[166:169] offset:32768
	s_waitcnt lgkmcnt(4)
	v_mfma_f32_16x16x32_bf16 v[4:7], v[56:59], v[126:129], v[4:7]
	ds_write_b128 v153, v[170:173] offset:36864
	s_waitcnt lgkmcnt(4)
	v_mfma_f32_16x16x32_bf16 v[8:11], v[56:59], v[130:133], v[8:11]
	ds_write_b128 v153, v[174:177] offset:49152
	global_load_dwordx4 v[166:169], v115, s[98:99] offset:1408
	s_waitcnt lgkmcnt(4)
	v_mfma_f32_16x16x32_bf16 v[12:15], v[56:59], v[134:137], v[12:15]
	ds_write_b128 v153, v[178:181] offset:53248
	global_load_dwordx4 v[170:173], v116, s[98:99] offset:1408
	s_waitcnt lgkmcnt(4)
	v_mfma_f32_16x16x32_bf16 v[16:19], v[60:63], v[118:121], v[16:19]
	ds_write_b128 v153, v[182:185] offset:57344
	global_load_dwordx4 v[174:177], v122, s[100:101] offset:1408
	v_mfma_f32_16x16x32_bf16 v[20:23], v[60:63], v[126:129], v[20:23]
	ds_write_b128 v153, v[186:189] offset:61440
	global_load_dwordx4 v[178:181], v123, s[100:101] offset:1408
	v_mfma_f32_16x16x32_bf16 v[24:27], v[60:63], v[130:133], v[24:27]
	global_load_dwordx4 v[182:185], v124, s[100:101] offset:1408
	v_mfma_f32_16x16x32_bf16 v[28:31], v[60:63], v[134:137], v[28:31]
	global_load_dwordx4 v[186:189], v146, s[100:101] offset:1408
	s_waitcnt lgkmcnt(0)
	s_barrier
	ds_read_b128 v[32:35], v239 offset:32768
	ds_read_b128 v[40:43], v241 offset:32768
	ds_read_b128 v[44:47], v241 offset:34816
	ds_read_b128 v[48:51], v241 offset:36864
	ds_read_b128 v[52:55], v241 offset:38912
	ds_read_b128 v[36:39], v239 offset:34816
	s_waitcnt lgkmcnt(4)
	v_mfma_f32_16x16x32_bf16 v[0:3], v[32:35], v[40:43], v[0:3]
	ds_read_b128 v[56:59], v240 offset:32768
	s_waitcnt lgkmcnt(4)
	v_mfma_f32_16x16x32_bf16 v[4:7], v[32:35], v[44:47], v[4:7]
	ds_read_b128 v[118:121], v242 offset:32768
	s_waitcnt lgkmcnt(4)
	v_mfma_f32_16x16x32_bf16 v[8:11], v[32:35], v[48:51], v[8:11]
	ds_read_b128 v[126:129], v242 offset:34816
	s_waitcnt lgkmcnt(4)
	v_mfma_f32_16x16x32_bf16 v[12:15], v[32:35], v[52:55], v[12:15]
	ds_read_b128 v[130:133], v242 offset:36864
	s_waitcnt lgkmcnt(4)
	v_mfma_f32_16x16x32_bf16 v[16:19], v[36:39], v[40:43], v[16:19]
	ds_read_b128 v[134:137], v242 offset:38912
	v_mfma_f32_16x16x32_bf16 v[20:23], v[36:39], v[44:47], v[20:23]
	ds_read_b128 v[60:63], v240 offset:34816
	v_mfma_f32_16x16x32_bf16 v[24:27], v[36:39], v[48:51], v[24:27]
	v_mfma_f32_16x16x32_bf16 v[28:31], v[36:39], v[52:55], v[28:31]
	s_waitcnt lgkmcnt(4)
	v_mfma_f32_16x16x32_bf16 v[0:3], v[56:59], v[118:121], v[0:3]
	s_waitcnt vmcnt(6)
	ds_write_b128 v153, v[138:141]
	s_waitcnt lgkmcnt(4)
	v_mfma_f32_16x16x32_bf16 v[4:7], v[56:59], v[126:129], v[4:7]
	ds_write_b128 v153, v[142:145] offset:4096
	s_waitcnt lgkmcnt(4)
	v_mfma_f32_16x16x32_bf16 v[8:11], v[56:59], v[130:133], v[8:11]
	ds_write_b128 v153, v[148:151] offset:16384
	global_load_dwordx4 v[138:141], v115, s[98:99] offset:1536
	s_waitcnt lgkmcnt(4)
	v_mfma_f32_16x16x32_bf16 v[12:15], v[56:59], v[134:137], v[12:15]
	ds_write_b128 v153, v[154:157] offset:20480
	global_load_dwordx4 v[142:145], v116, s[98:99] offset:1536
	s_waitcnt lgkmcnt(4)
	v_mfma_f32_16x16x32_bf16 v[16:19], v[60:63], v[118:121], v[16:19]
	ds_write_b128 v153, v[158:161] offset:24576
	global_load_dwordx4 v[148:151], v122, s[100:101] offset:1536
	v_mfma_f32_16x16x32_bf16 v[20:23], v[60:63], v[126:129], v[20:23]
	ds_write_b128 v153, v[162:165] offset:28672
	global_load_dwordx4 v[154:157], v123, s[100:101] offset:1536
	v_mfma_f32_16x16x32_bf16 v[24:27], v[60:63], v[130:133], v[24:27]
	global_load_dwordx4 v[158:161], v124, s[100:101] offset:1536
	v_mfma_f32_16x16x32_bf16 v[28:31], v[60:63], v[134:137], v[28:31]
	global_load_dwordx4 v[162:165], v146, s[100:101] offset:1536
	s_waitcnt lgkmcnt(0)
	s_barrier
	ds_read_b128 v[32:35], v239
	ds_read_b128 v[40:43], v241
	ds_read_b128 v[44:47], v241 offset:2048
	ds_read_b128 v[48:51], v241 offset:4096
	ds_read_b128 v[52:55], v241 offset:6144
	ds_read_b128 v[36:39], v239 offset:2048
	s_waitcnt lgkmcnt(4)
	v_mfma_f32_16x16x32_bf16 v[0:3], v[32:35], v[40:43], v[0:3]
	ds_read_b128 v[56:59], v240
	s_waitcnt lgkmcnt(4)
	v_mfma_f32_16x16x32_bf16 v[4:7], v[32:35], v[44:47], v[4:7]
	ds_read_b128 v[118:121], v242
	s_waitcnt lgkmcnt(4)
	v_mfma_f32_16x16x32_bf16 v[8:11], v[32:35], v[48:51], v[8:11]
	ds_read_b128 v[126:129], v242 offset:2048
	s_waitcnt lgkmcnt(4)
	v_mfma_f32_16x16x32_bf16 v[12:15], v[32:35], v[52:55], v[12:15]
	ds_read_b128 v[130:133], v242 offset:4096
	s_waitcnt lgkmcnt(4)
	v_mfma_f32_16x16x32_bf16 v[16:19], v[36:39], v[40:43], v[16:19]
	ds_read_b128 v[134:137], v242 offset:6144
	v_mfma_f32_16x16x32_bf16 v[20:23], v[36:39], v[44:47], v[20:23]
	ds_read_b128 v[60:63], v240 offset:2048
	v_mfma_f32_16x16x32_bf16 v[24:27], v[36:39], v[48:51], v[24:27]
	v_mfma_f32_16x16x32_bf16 v[28:31], v[36:39], v[52:55], v[28:31]
	s_waitcnt lgkmcnt(4)
	v_mfma_f32_16x16x32_bf16 v[0:3], v[56:59], v[118:121], v[0:3]
	s_waitcnt vmcnt(6)
	ds_write_b128 v153, v[166:169] offset:32768
	s_waitcnt lgkmcnt(4)
	v_mfma_f32_16x16x32_bf16 v[4:7], v[56:59], v[126:129], v[4:7]
	ds_write_b128 v153, v[170:173] offset:36864
	s_waitcnt lgkmcnt(4)
	v_mfma_f32_16x16x32_bf16 v[8:11], v[56:59], v[130:133], v[8:11]
	ds_write_b128 v153, v[174:177] offset:49152
	global_load_dwordx4 v[166:169], v115, s[98:99] offset:1664
	s_waitcnt lgkmcnt(4)
	v_mfma_f32_16x16x32_bf16 v[12:15], v[56:59], v[134:137], v[12:15]
	ds_write_b128 v153, v[178:181] offset:53248
	global_load_dwordx4 v[170:173], v116, s[98:99] offset:1664
	s_waitcnt lgkmcnt(4)
	v_mfma_f32_16x16x32_bf16 v[16:19], v[60:63], v[118:121], v[16:19]
	ds_write_b128 v153, v[182:185] offset:57344
	global_load_dwordx4 v[174:177], v122, s[100:101] offset:1664
	v_mfma_f32_16x16x32_bf16 v[20:23], v[60:63], v[126:129], v[20:23]
	ds_write_b128 v153, v[186:189] offset:61440
	global_load_dwordx4 v[178:181], v123, s[100:101] offset:1664
	v_mfma_f32_16x16x32_bf16 v[24:27], v[60:63], v[130:133], v[24:27]
	global_load_dwordx4 v[182:185], v124, s[100:101] offset:1664
	v_mfma_f32_16x16x32_bf16 v[28:31], v[60:63], v[134:137], v[28:31]
	global_load_dwordx4 v[186:189], v146, s[100:101] offset:1664
	s_waitcnt lgkmcnt(0)
	s_barrier
	ds_read_b128 v[32:35], v239 offset:32768
	ds_read_b128 v[40:43], v241 offset:32768
	ds_read_b128 v[44:47], v241 offset:34816
	ds_read_b128 v[48:51], v241 offset:36864
	ds_read_b128 v[52:55], v241 offset:38912
	ds_read_b128 v[36:39], v239 offset:34816
	s_waitcnt lgkmcnt(4)
	v_mfma_f32_16x16x32_bf16 v[0:3], v[32:35], v[40:43], v[0:3]
	ds_read_b128 v[56:59], v240 offset:32768
	s_waitcnt lgkmcnt(4)
	v_mfma_f32_16x16x32_bf16 v[4:7], v[32:35], v[44:47], v[4:7]
	ds_read_b128 v[118:121], v242 offset:32768
	s_waitcnt lgkmcnt(4)
	v_mfma_f32_16x16x32_bf16 v[8:11], v[32:35], v[48:51], v[8:11]
	ds_read_b128 v[126:129], v242 offset:34816
	s_waitcnt lgkmcnt(4)
	v_mfma_f32_16x16x32_bf16 v[12:15], v[32:35], v[52:55], v[12:15]
	ds_read_b128 v[130:133], v242 offset:36864
	s_waitcnt lgkmcnt(4)
	v_mfma_f32_16x16x32_bf16 v[16:19], v[36:39], v[40:43], v[16:19]
	ds_read_b128 v[134:137], v242 offset:38912
	v_mfma_f32_16x16x32_bf16 v[20:23], v[36:39], v[44:47], v[20:23]
	ds_read_b128 v[60:63], v240 offset:34816
	v_mfma_f32_16x16x32_bf16 v[24:27], v[36:39], v[48:51], v[24:27]
	v_mfma_f32_16x16x32_bf16 v[28:31], v[36:39], v[52:55], v[28:31]
	s_waitcnt lgkmcnt(4)
	v_mfma_f32_16x16x32_bf16 v[0:3], v[56:59], v[118:121], v[0:3]
	s_waitcnt vmcnt(6)
	ds_write_b128 v153, v[138:141]
	s_waitcnt lgkmcnt(4)
	v_mfma_f32_16x16x32_bf16 v[4:7], v[56:59], v[126:129], v[4:7]
	ds_write_b128 v153, v[142:145] offset:4096
	s_waitcnt lgkmcnt(4)
	v_mfma_f32_16x16x32_bf16 v[8:11], v[56:59], v[130:133], v[8:11]
	ds_write_b128 v153, v[148:151] offset:16384
	global_load_dwordx4 v[138:141], v115, s[98:99] offset:1792
	s_waitcnt lgkmcnt(4)
	v_mfma_f32_16x16x32_bf16 v[12:15], v[56:59], v[134:137], v[12:15]
	ds_write_b128 v153, v[154:157] offset:20480
	global_load_dwordx4 v[142:145], v116, s[98:99] offset:1792
	s_waitcnt lgkmcnt(4)
	v_mfma_f32_16x16x32_bf16 v[16:19], v[60:63], v[118:121], v[16:19]
	ds_write_b128 v153, v[158:161] offset:24576
	global_load_dwordx4 v[148:151], v122, s[100:101] offset:1792
	v_mfma_f32_16x16x32_bf16 v[20:23], v[60:63], v[126:129], v[20:23]
	ds_write_b128 v153, v[162:165] offset:28672
	global_load_dwordx4 v[154:157], v123, s[100:101] offset:1792
	v_mfma_f32_16x16x32_bf16 v[24:27], v[60:63], v[130:133], v[24:27]
	global_load_dwordx4 v[158:161], v124, s[100:101] offset:1792
	v_mfma_f32_16x16x32_bf16 v[28:31], v[60:63], v[134:137], v[28:31]
	global_load_dwordx4 v[162:165], v146, s[100:101] offset:1792
	s_waitcnt lgkmcnt(0)
	s_barrier
	ds_read_b128 v[32:35], v239
	ds_read_b128 v[40:43], v241
	ds_read_b128 v[44:47], v241 offset:2048
	ds_read_b128 v[48:51], v241 offset:4096
	ds_read_b128 v[52:55], v241 offset:6144
	ds_read_b128 v[36:39], v239 offset:2048
	s_waitcnt lgkmcnt(4)
	v_mfma_f32_16x16x32_bf16 v[0:3], v[32:35], v[40:43], v[0:3]
	ds_read_b128 v[56:59], v240
	s_waitcnt lgkmcnt(4)
	v_mfma_f32_16x16x32_bf16 v[4:7], v[32:35], v[44:47], v[4:7]
	ds_read_b128 v[118:121], v242
	s_waitcnt lgkmcnt(4)
	v_mfma_f32_16x16x32_bf16 v[8:11], v[32:35], v[48:51], v[8:11]
	ds_read_b128 v[126:129], v242 offset:2048
	s_waitcnt lgkmcnt(4)
	v_mfma_f32_16x16x32_bf16 v[12:15], v[32:35], v[52:55], v[12:15]
	ds_read_b128 v[130:133], v242 offset:4096
	s_waitcnt lgkmcnt(4)
	v_mfma_f32_16x16x32_bf16 v[16:19], v[36:39], v[40:43], v[16:19]
	ds_read_b128 v[134:137], v242 offset:6144
	v_mfma_f32_16x16x32_bf16 v[20:23], v[36:39], v[44:47], v[20:23]
	ds_read_b128 v[60:63], v240 offset:2048
	v_mfma_f32_16x16x32_bf16 v[24:27], v[36:39], v[48:51], v[24:27]
	v_mfma_f32_16x16x32_bf16 v[28:31], v[36:39], v[52:55], v[28:31]
	s_waitcnt lgkmcnt(4)
	v_mfma_f32_16x16x32_bf16 v[0:3], v[56:59], v[118:121], v[0:3]
	s_waitcnt vmcnt(6)
	ds_write_b128 v153, v[166:169] offset:32768
	s_waitcnt lgkmcnt(4)
	v_mfma_f32_16x16x32_bf16 v[4:7], v[56:59], v[126:129], v[4:7]
	ds_write_b128 v153, v[170:173] offset:36864
	s_waitcnt lgkmcnt(4)
	v_mfma_f32_16x16x32_bf16 v[8:11], v[56:59], v[130:133], v[8:11]
	ds_write_b128 v153, v[174:177] offset:49152
	global_load_dwordx4 v[166:169], v115, s[98:99] offset:1920
	s_waitcnt lgkmcnt(4)
	v_mfma_f32_16x16x32_bf16 v[12:15], v[56:59], v[134:137], v[12:15]
	ds_write_b128 v153, v[178:181] offset:53248
	global_load_dwordx4 v[170:173], v116, s[98:99] offset:1920
	s_waitcnt lgkmcnt(4)
	v_mfma_f32_16x16x32_bf16 v[16:19], v[60:63], v[118:121], v[16:19]
	ds_write_b128 v153, v[182:185] offset:57344
	global_load_dwordx4 v[174:177], v122, s[100:101] offset:1920
	v_mfma_f32_16x16x32_bf16 v[20:23], v[60:63], v[126:129], v[20:23]
	ds_write_b128 v153, v[186:189] offset:61440
	global_load_dwordx4 v[178:181], v123, s[100:101] offset:1920
	v_mfma_f32_16x16x32_bf16 v[24:27], v[60:63], v[130:133], v[24:27]
	global_load_dwordx4 v[182:185], v124, s[100:101] offset:1920
	v_mfma_f32_16x16x32_bf16 v[28:31], v[60:63], v[134:137], v[28:31]
	global_load_dwordx4 v[186:189], v146, s[100:101] offset:1920
	s_waitcnt lgkmcnt(0)
	s_barrier
	ds_read_b128 v[32:35], v239 offset:32768
	ds_read_b128 v[40:43], v241 offset:32768
	ds_read_b128 v[44:47], v241 offset:34816
	ds_read_b128 v[48:51], v241 offset:36864
	ds_read_b128 v[52:55], v241 offset:38912
	ds_read_b128 v[36:39], v239 offset:34816
	s_waitcnt lgkmcnt(4)
	v_mfma_f32_16x16x32_bf16 v[0:3], v[32:35], v[40:43], v[0:3]
	ds_read_b128 v[56:59], v240 offset:32768
	s_waitcnt lgkmcnt(4)
	v_mfma_f32_16x16x32_bf16 v[4:7], v[32:35], v[44:47], v[4:7]
	ds_read_b128 v[118:121], v242 offset:32768
	s_waitcnt lgkmcnt(4)
	v_mfma_f32_16x16x32_bf16 v[8:11], v[32:35], v[48:51], v[8:11]
	ds_read_b128 v[126:129], v242 offset:34816
	s_waitcnt lgkmcnt(4)
	v_mfma_f32_16x16x32_bf16 v[12:15], v[32:35], v[52:55], v[12:15]
	ds_read_b128 v[130:133], v242 offset:36864
	s_waitcnt lgkmcnt(4)
	v_mfma_f32_16x16x32_bf16 v[16:19], v[36:39], v[40:43], v[16:19]
	ds_read_b128 v[134:137], v242 offset:38912
	v_mfma_f32_16x16x32_bf16 v[20:23], v[36:39], v[44:47], v[20:23]
	ds_read_b128 v[60:63], v240 offset:34816
	v_mfma_f32_16x16x32_bf16 v[24:27], v[36:39], v[48:51], v[24:27]
	v_mfma_f32_16x16x32_bf16 v[28:31], v[36:39], v[52:55], v[28:31]
	s_waitcnt lgkmcnt(4)
	v_mfma_f32_16x16x32_bf16 v[0:3], v[56:59], v[118:121], v[0:3]
	s_waitcnt vmcnt(6)
	ds_write_b128 v153, v[138:141]
	s_waitcnt lgkmcnt(4)
	v_mfma_f32_16x16x32_bf16 v[4:7], v[56:59], v[126:129], v[4:7]
	ds_write_b128 v153, v[142:145] offset:4096
	s_waitcnt lgkmcnt(4)
	v_mfma_f32_16x16x32_bf16 v[8:11], v[56:59], v[130:133], v[8:11]
	ds_write_b128 v153, v[148:151] offset:16384
	s_waitcnt lgkmcnt(4)
	v_mfma_f32_16x16x32_bf16 v[12:15], v[56:59], v[134:137], v[12:15]
	ds_write_b128 v153, v[154:157] offset:20480
	s_waitcnt lgkmcnt(4)
	v_mfma_f32_16x16x32_bf16 v[16:19], v[60:63], v[118:121], v[16:19]
	ds_write_b128 v153, v[158:161] offset:24576
	v_mfma_f32_16x16x32_bf16 v[20:23], v[60:63], v[126:129], v[20:23]
	ds_write_b128 v153, v[162:165] offset:28672
	v_mfma_f32_16x16x32_bf16 v[24:27], v[60:63], v[130:133], v[24:27]
	v_mfma_f32_16x16x32_bf16 v[28:31], v[60:63], v[134:137], v[28:31]
	s_waitcnt lgkmcnt(0)
	s_barrier
	ds_read_b128 v[32:35], v239
	ds_read_b128 v[40:43], v241
	ds_read_b128 v[44:47], v241 offset:2048
	ds_read_b128 v[48:51], v241 offset:4096
	ds_read_b128 v[52:55], v241 offset:6144
	ds_read_b128 v[36:39], v239 offset:2048
	s_waitcnt lgkmcnt(4)
	v_mfma_f32_16x16x32_bf16 v[0:3], v[32:35], v[40:43], v[0:3]
	ds_read_b128 v[56:59], v240
	s_waitcnt lgkmcnt(4)
	v_mfma_f32_16x16x32_bf16 v[4:7], v[32:35], v[44:47], v[4:7]
	ds_read_b128 v[118:121], v242
	s_waitcnt lgkmcnt(4)
	v_mfma_f32_16x16x32_bf16 v[8:11], v[32:35], v[48:51], v[8:11]
	ds_read_b128 v[126:129], v242 offset:2048
	s_waitcnt lgkmcnt(4)
	v_mfma_f32_16x16x32_bf16 v[12:15], v[32:35], v[52:55], v[12:15]
	ds_read_b128 v[130:133], v242 offset:4096
	s_waitcnt lgkmcnt(4)
	v_mfma_f32_16x16x32_bf16 v[16:19], v[36:39], v[40:43], v[16:19]
	ds_read_b128 v[134:137], v242 offset:6144
	v_mfma_f32_16x16x32_bf16 v[20:23], v[36:39], v[44:47], v[20:23]
	ds_read_b128 v[60:63], v240 offset:2048
	v_mfma_f32_16x16x32_bf16 v[24:27], v[36:39], v[48:51], v[24:27]
	v_mfma_f32_16x16x32_bf16 v[28:31], v[36:39], v[52:55], v[28:31]
	s_waitcnt lgkmcnt(4)
	v_mfma_f32_16x16x32_bf16 v[0:3], v[56:59], v[118:121], v[0:3]
	s_waitcnt vmcnt(0)
	ds_write_b128 v153, v[166:169] offset:32768
	s_waitcnt lgkmcnt(4)
	v_mfma_f32_16x16x32_bf16 v[4:7], v[56:59], v[126:129], v[4:7]
	ds_write_b128 v153, v[170:173] offset:36864
	s_waitcnt lgkmcnt(4)
	v_mfma_f32_16x16x32_bf16 v[8:11], v[56:59], v[130:133], v[8:11]
	ds_write_b128 v153, v[174:177] offset:49152
	s_waitcnt lgkmcnt(4)
	v_mfma_f32_16x16x32_bf16 v[12:15], v[56:59], v[134:137], v[12:15]
	ds_write_b128 v153, v[178:181] offset:53248
	s_waitcnt lgkmcnt(4)
	v_mfma_f32_16x16x32_bf16 v[16:19], v[60:63], v[118:121], v[16:19]
	ds_write_b128 v153, v[182:185] offset:57344
	v_mfma_f32_16x16x32_bf16 v[20:23], v[60:63], v[126:129], v[20:23]
	ds_write_b128 v153, v[186:189] offset:61440
	v_mfma_f32_16x16x32_bf16 v[24:27], v[60:63], v[130:133], v[24:27]
	v_mfma_f32_16x16x32_bf16 v[28:31], v[60:63], v[134:137], v[28:31]
	s_waitcnt lgkmcnt(0)
	s_barrier
	ds_read_b128 v[32:35], v239 offset:32768
	ds_read_b128 v[40:43], v241 offset:32768
	ds_read_b128 v[44:47], v241 offset:34816
	ds_read_b128 v[48:51], v241 offset:36864
	ds_read_b128 v[52:55], v241 offset:38912
	ds_read_b128 v[36:39], v239 offset:34816
	s_waitcnt lgkmcnt(4)
	v_mfma_f32_16x16x32_bf16 v[0:3], v[32:35], v[40:43], v[0:3]
	ds_read_b128 v[56:59], v240 offset:32768
	s_waitcnt lgkmcnt(4)
	v_mfma_f32_16x16x32_bf16 v[4:7], v[32:35], v[44:47], v[4:7]
	ds_read_b128 v[118:121], v242 offset:32768
	s_waitcnt lgkmcnt(4)
	v_mfma_f32_16x16x32_bf16 v[8:11], v[32:35], v[48:51], v[8:11]
	ds_read_b128 v[126:129], v242 offset:34816
	s_waitcnt lgkmcnt(4)
	v_mfma_f32_16x16x32_bf16 v[12:15], v[32:35], v[52:55], v[12:15]
	ds_read_b128 v[130:133], v242 offset:36864
	s_waitcnt lgkmcnt(4)
	v_mfma_f32_16x16x32_bf16 v[16:19], v[36:39], v[40:43], v[16:19]
	ds_read_b128 v[134:137], v242 offset:38912
	v_mfma_f32_16x16x32_bf16 v[20:23], v[36:39], v[44:47], v[20:23]
	ds_read_b128 v[60:63], v240 offset:34816
	v_mfma_f32_16x16x32_bf16 v[24:27], v[36:39], v[48:51], v[24:27]
	v_mfma_f32_16x16x32_bf16 v[28:31], v[36:39], v[52:55], v[28:31]
	s_waitcnt lgkmcnt(4)
	v_mfma_f32_16x16x32_bf16 v[0:3], v[56:59], v[118:121], v[0:3]
	s_waitcnt lgkmcnt(3)
	v_mfma_f32_16x16x32_bf16 v[4:7], v[56:59], v[126:129], v[4:7]
	s_waitcnt lgkmcnt(2)
	v_mfma_f32_16x16x32_bf16 v[8:11], v[56:59], v[130:133], v[8:11]
	s_waitcnt lgkmcnt(1)
	v_mfma_f32_16x16x32_bf16 v[12:15], v[56:59], v[134:137], v[12:15]
	s_waitcnt lgkmcnt(0)
	v_mfma_f32_16x16x32_bf16 v[16:19], v[60:63], v[118:121], v[16:19]
	v_mfma_f32_16x16x32_bf16 v[20:23], v[60:63], v[126:129], v[20:23]
	v_mfma_f32_16x16x32_bf16 v[24:27], v[60:63], v[130:133], v[24:27]
	v_mfma_f32_16x16x32_bf16 v[28:31], v[60:63], v[134:137], v[28:31]
	s_waitcnt lgkmcnt(0)
	s_barrier
	s_nop 15
	ds_write_b32 v243, v0
	ds_write_b32 v243, v1 offset:528
	ds_write_b32 v243, v2 offset:1056
	ds_write_b32 v243, v3 offset:1584
	ds_write_b32 v243, v4 offset:64
	ds_write_b32 v243, v5 offset:592
	ds_write_b32 v243, v6 offset:1120
	ds_write_b32 v243, v7 offset:1648
	ds_write_b32 v243, v8 offset:128
	ds_write_b32 v243, v9 offset:656
	ds_write_b32 v243, v10 offset:1184
	ds_write_b32 v243, v11 offset:1712
	ds_write_b32 v243, v12 offset:192
	ds_write_b32 v243, v13 offset:720
	ds_write_b32 v243, v14 offset:1248
	ds_write_b32 v243, v15 offset:1776
	ds_write_b32 v243, v16 offset:8448
	ds_write_b32 v243, v17 offset:8976
	ds_write_b32 v243, v18 offset:9504
	ds_write_b32 v243, v19 offset:10032
	ds_write_b32 v243, v20 offset:8512
	ds_write_b32 v243, v21 offset:9040
	ds_write_b32 v243, v22 offset:9568
	ds_write_b32 v243, v23 offset:10096
	ds_write_b32 v243, v24 offset:8576
	ds_write_b32 v243, v25 offset:9104
	ds_write_b32 v243, v26 offset:9632
	ds_write_b32 v243, v27 offset:10160
	ds_write_b32 v243, v28 offset:8640
	ds_write_b32 v243, v29 offset:9168
	ds_write_b32 v243, v30 offset:9696
	ds_write_b32 v243, v31 offset:10224
	v_add_lshl_u32 v64, s14, v105, 11
	v_mov_b64_e32 v[48:49], v[64:65]
	v_mov_b32_e32 v49, v65
	v_lshl_add_u64 v[16:17], v[68:69], 0, v[48:49]
	v_lshl_add_u64 v[80:81], v[68:69], 0, v[48:49]
	s_and_b32 s10, s1, 0x7fffffc0
	v_readlane_b32 s44, v238, 32
	v_readlane_b32 s56, v238, 44
	v_readlane_b32 s57, v238, 45
	v_readlane_b32 s45, v238, 33
	v_readlane_b32 s46, v238, 34
	v_readlane_b32 s47, v238, 35
	v_readlane_b32 s48, v238, 36
	v_readlane_b32 s49, v238, 37
	v_readlane_b32 s50, v238, 38
	v_readlane_b32 s51, v238, 39
	v_readlane_b32 s52, v238, 40
	v_readlane_b32 s53, v238, 41
	v_readlane_b32 s54, v238, 42
	v_readlane_b32 s55, v238, 43
	v_readlane_b32 s58, v238, 46
	v_readlane_b32 s59, v238, 47
	v_add_lshl_u32 v33, v112, s10, 11
	v_add_lshl_u32 v32, v90, s10, 11
	v_add_lshl_u32 v34, v93, s10, 11
	v_add_lshl_u32 v36, v109, s10, 11
	s_mov_b32 s10, 0
	v_or_b32_e32 v0, s20, v82
	v_lshlrev_b32_e32 v64, 1, v0
	v_lshl_add_u64 v[0:1], s[56:57], 0, v[64:65]
	v_mov_b32_e32 v64, v33
	s_waitcnt lgkmcnt(0)
	s_barrier
